# in-proj, QKV and FFN-up GEMM k-loops: tile loads addressed as scalar base plus per-lane 32-bit offset (12 64-bit VALU address adds and hazard nops per k-step removed); attention K reads issued before
# speedup vs baseline: 1.0262x; 1.0262x over previous
.LBB0_249:
	s_and_b32 s2, s16, 15
	s_lshl_b32 s2, s2, 7
	v_add_u32_e32 v0, s2, v142
	v_ashrrev_i32_e32 v1, 31, v0
	v_lshlrev_b64 v[0:1], 11, v[0:1]
	v_lshl_add_u64 v[116:117], v[110:111], 0, v[0:1]
	v_add_u32_e32 v0, s2, v143
	v_ashrrev_i32_e32 v1, 31, v0
	v_lshlrev_b64 v[0:1], 11, v[0:1]
	v_lshl_add_u64 v[118:119], v[110:111], 0, v[0:1]
	v_add_u32_e32 v0, s2, v144
	v_ashrrev_i32_e32 v1, 31, v0
	v_lshlrev_b64 v[0:1], 11, v[0:1]
	v_lshl_add_u64 v[120:121], v[110:111], 0, v[0:1]
	v_add_u32_e32 v0, s2, v145
	v_ashrrev_i32_e32 v1, 31, v0
	s_lshl_b32 s2, s15, 11
	v_lshlrev_b64 v[0:1], 11, v[0:1]
	s_and_b32 s50, s2, 0x7c0000
	s_and_b32 s2, s15, 0xf80
	v_lshl_add_u64 v[122:123], v[110:111], 0, v[0:1]
	v_add_u32_e32 v0, s2, v97
	v_ashrrev_i32_e32 v1, 31, v0
	v_lshlrev_b64 v[0:1], 11, v[0:1]
	v_lshl_add_u64 v[126:127], v[114:115], 0, v[0:1]
	v_add_u32_e32 v0, s2, v146
	v_ashrrev_i32_e32 v1, 31, v0
	v_lshlrev_b64 v[0:1], 11, v[0:1]
	v_lshl_add_u64 v[128:129], v[114:115], 0, v[0:1]
	v_add_u32_e32 v0, s2, v147
	s_and_b32 s2, s17, 15
	v_readlane_b32 s3, v253, 46
	v_ashrrev_i32_e32 v1, 31, v0
	s_or_b32 s2, s2, s3
	v_lshlrev_b64 v[0:1], 11, v[0:1]
	s_lshl_b32 s3, s2, 7
	v_lshl_add_u64 v[130:131], v[114:115], 0, v[0:1]
	v_add_u32_e32 v0, s3, v96
	v_ashrrev_i32_e32 v1, 31, v0
	v_lshlrev_b64 v[0:1], 11, v[0:1]
	v_lshl_add_u64 v[12:13], v[98:99], 0, v[0:1]
	s_mov_b32 s2, 0x10000
	v_add_co_u32_e32 v4, vcc, s2, v12
	s_lshl_b32 s6, s17, 3
	s_nop 0
	v_addc_co_u32_e32 v5, vcc, 0, v13, vcc
	s_mov_b32 s2, 0x20000
	v_add_co_u32_e32 v8, vcc, s2, v12
	s_and_b32 s2, s6, 0xf80
	v_add_u32_e32 v16, s2, v96
	v_ashrrev_i32_e32 v17, 31, v16
	v_lshlrev_b64 v[16:17], 11, v[16:17]
	v_addc_co_u32_e32 v9, vcc, 0, v13, vcc
	v_lshl_add_u64 v[28:29], v[100:101], 0, v[16:17]
	global_load_dwordx4 v[0:3], v[12:13], off sc1
	global_load_dwordx4 v[16:19], v[28:29], off sc1
	v_add_co_u32_e32 v12, vcc, 0x30000, v12
	global_load_dwordx4 v[4:7], v[4:5], off sc1
	s_nop 0
	v_addc_co_u32_e32 v13, vcc, 0, v13, vcc
	v_add_co_u32_e32 v20, vcc, 0x10000, v28
	global_load_dwordx4 v[8:11], v[8:9], off sc1
	s_nop 0
	v_addc_co_u32_e32 v21, vcc, 0, v29, vcc
	v_add_co_u32_e32 v24, vcc, 0x20000, v28
	global_load_dwordx4 v[12:15], v[12:13], off sc1
	s_nop 0
	v_addc_co_u32_e32 v25, vcc, 0, v29, vcc
	v_add_co_u32_e32 v28, vcc, 0x30000, v28
	global_load_dwordx4 v[20:23], v[20:21], off sc1
	s_nop 0
	v_addc_co_u32_e32 v29, vcc, 0, v29, vcc
	global_load_dwordx4 v[24:27], v[24:25], off sc1
	v_mov_b32_e32 v40, 0
	global_load_dwordx4 v[28:31], v[28:29], off sc1
	v_lshl_add_u64 v[124:125], v[112:113], 0, s[50:51]
	s_mov_b64 s[6:7], 0
	v_mov_b32_e32 v41, v40
	v_mov_b32_e32 v42, v40
	v_mov_b32_e32 v43, v40
	v_mov_b32_e32 v68, v40
	v_mov_b32_e32 v69, v40
	v_mov_b32_e32 v70, v40
	v_mov_b32_e32 v71, v40
	v_mov_b32_e32 v72, v40
	v_mov_b32_e32 v73, v40
	v_mov_b32_e32 v74, v40
	v_mov_b32_e32 v75, v40
	v_mov_b32_e32 v76, v40
	v_mov_b32_e32 v77, v40
	v_mov_b32_e32 v78, v40
	v_mov_b32_e32 v79, v40
	v_mov_b32_e32 v36, v40
	v_mov_b32_e32 v37, v40
	v_mov_b32_e32 v38, v40
	v_mov_b32_e32 v39, v40
	v_mov_b32_e32 v44, v40
	v_mov_b32_e32 v45, v40
	v_mov_b32_e32 v46, v40
	v_mov_b32_e32 v47, v40
	v_mov_b32_e32 v48, v40
	v_mov_b32_e32 v49, v40
	v_mov_b32_e32 v50, v40
	v_mov_b32_e32 v51, v40
	v_mov_b32_e32 v52, v40
	v_mov_b32_e32 v53, v40
	v_mov_b32_e32 v54, v40
	v_mov_b32_e32 v55, v40
	v_mov_b32_e32 v56, v40
	v_mov_b32_e32 v57, v40
	v_mov_b32_e32 v58, v40
	v_mov_b32_e32 v59, v40
	v_mov_b32_e32 v60, v40
	v_mov_b32_e32 v61, v40
	v_mov_b32_e32 v62, v40
	v_mov_b32_e32 v63, v40
	v_mov_b32_e32 v64, v40
	v_mov_b32_e32 v65, v40
	v_mov_b32_e32 v66, v40
	v_mov_b32_e32 v67, v40
	v_mov_b32_e32 v32, v40
	v_mov_b32_e32 v33, v40
	v_mov_b32_e32 v34, v40
	v_mov_b32_e32 v35, v40
	v_mov_b32_e32 v84, v40
	v_mov_b32_e32 v85, v40
	v_mov_b32_e32 v86, v40
	v_mov_b32_e32 v87, v40
	v_mov_b32_e32 v88, v40
	v_mov_b32_e32 v89, v40
	v_mov_b32_e32 v90, v40
	v_mov_b32_e32 v91, v40
	v_mov_b32_e32 v92, v40
	v_mov_b32_e32 v93, v40
	v_mov_b32_e32 v94, v40
	v_mov_b32_e32 v95, v40
	v_mov_b32_e32 v80, v40
	v_mov_b32_e32 v81, v40
	v_mov_b32_e32 v82, v40
	v_mov_b32_e32 v83, v40
	v_readfirstlane_b32 s76, v116
	v_readfirstlane_b32 s77, v117
	s_sub_u32 s76, s76, 0x100000
	s_subb_u32 s77, s77, 0
	v_readfirstlane_b32 s78, v124
	v_readfirstlane_b32 s79, v125
	s_sub_u32 s78, s78, 0x100000
	s_subb_u32 s79, s79, 0
	v_subrev_u32_e32 v116, s76, v116
	v_subrev_u32_e32 v118, s76, v118
	v_subrev_u32_e32 v120, s76, v120
	v_subrev_u32_e32 v122, s76, v122
	v_subrev_u32_e32 v124, s78, v124
	v_subrev_u32_e32 v126, s78, v126
	v_subrev_u32_e32 v128, s78, v128
	v_subrev_u32_e32 v130, s78, v130
.LBB0_250:
	s_barrier
	s_waitcnt vmcnt(7)
	ds_write_b128 v148, v[0:3]
	s_waitcnt vmcnt(5)
	ds_write_b128 v148, v[4:7] offset:5120
	s_waitcnt vmcnt(4)
	ds_write_b128 v148, v[8:11] offset:10240
	s_waitcnt vmcnt(3)
	ds_write_b128 v148, v[12:15] offset:15360
	ds_write_b128 v148, v[16:19] offset:20480
	s_waitcnt vmcnt(2)
	ds_write_b128 v148, v[20:23] offset:25600
	s_waitcnt vmcnt(1)
	ds_write_b128 v148, v[24:27] offset:30720
	s_waitcnt vmcnt(0)
	ds_write_b128 v148, v[28:31] offset:35840
	s_add_u32 s80, s76, s6
	s_addc_u32 s81, s77, s7
	s_add_u32 s82, s78, s6
	s_addc_u32 s83, s79, s7
	s_waitcnt lgkmcnt(0)
	s_barrier
	global_load_dwordx4 v[0:3], v116, s[80:81] sc1
	global_load_dwordx4 v[4:7], v118, s[80:81] sc1
	global_load_dwordx4 v[8:11], v120, s[80:81] sc1
	global_load_dwordx4 v[12:15], v122, s[80:81] sc1
	global_load_dwordx4 v[16:19], v124, s[82:83] sc1
	global_load_dwordx4 v[20:23], v126, s[82:83] sc1
	global_load_dwordx4 v[24:27], v128, s[82:83] sc1
	global_load_dwordx4 v[28:31], v130, s[82:83] sc1
	ds_read_b128 v[150:153], v149 offset:20480
	ds_read_b128 v[158:161], v149 offset:23040
	ds_read_b128 v[162:165], v149 offset:25600
	ds_read_b128 v[166:169], v149 offset:28160
	ds_read_b128 v[154:157], v134
	ds_read_b128 v[170:173], v134 offset:2560
	ds_read_b128 v[174:177], v134 offset:5120
	ds_read_b128 v[178:181], v134 offset:7680
	ds_read_b128 v[182:185], v149 offset:20544
	ds_read_b128 v[186:189], v149 offset:23104
	ds_read_b128 v[202:205], v149 offset:25664
	ds_read_b128 v[206:209], v149 offset:28224
	s_add_u32 s6, s6, 0x80
	s_addc_u32 s7, s7, 0
	s_waitcnt lgkmcnt(7)
	v_mfma_f32_16x16x32_bf16 v[32:35], v[150:153], v[154:157], v[32:35]
	v_mfma_f32_16x16x32_bf16 v[64:67], v[158:161], v[154:157], v[64:67]
	v_mfma_f32_16x16x32_bf16 v[60:63], v[162:165], v[154:157], v[60:63]
	v_mfma_f32_16x16x32_bf16 v[56:59], v[166:169], v[154:157], v[56:59]
	ds_read_b128 v[154:157], v134 offset:64
	s_waitcnt lgkmcnt(7)
	v_mfma_f32_16x16x32_bf16 v[52:55], v[150:153], v[170:173], v[52:55]
	v_mfma_f32_16x16x32_bf16 v[48:51], v[158:161], v[170:173], v[48:51]
	v_mfma_f32_16x16x32_bf16 v[44:47], v[162:165], v[170:173], v[44:47]
	v_mfma_f32_16x16x32_bf16 v[36:39], v[166:169], v[170:173], v[36:39]
	ds_read_b128 v[170:173], v134 offset:2624
	s_waitcnt lgkmcnt(7)
	v_mfma_f32_16x16x32_bf16 v[76:79], v[150:153], v[174:177], v[76:79]
	v_mfma_f32_16x16x32_bf16 v[72:75], v[158:161], v[174:177], v[72:75]
	v_mfma_f32_16x16x32_bf16 v[68:71], v[162:165], v[174:177], v[68:71]
	v_mfma_f32_16x16x32_bf16 v[40:43], v[166:169], v[174:177], v[40:43]
	ds_read_b128 v[174:177], v134 offset:5184
	s_waitcnt lgkmcnt(7)
	v_mfma_f32_16x16x32_bf16 v[84:87], v[150:153], v[178:181], v[84:87]
	v_mfma_f32_16x16x32_bf16 v[88:91], v[158:161], v[178:181], v[88:91]
	v_mfma_f32_16x16x32_bf16 v[92:95], v[162:165], v[178:181], v[92:95]
	v_mfma_f32_16x16x32_bf16 v[80:83], v[166:169], v[178:181], v[80:83]
	ds_read_b128 v[178:181], v134 offset:7744
	s_waitcnt lgkmcnt(3)
	v_mfma_f32_16x16x32_bf16 v[32:35], v[182:185], v[154:157], v[32:35]
	v_mfma_f32_16x16x32_bf16 v[64:67], v[186:189], v[154:157], v[64:67]
	v_mfma_f32_16x16x32_bf16 v[60:63], v[202:205], v[154:157], v[60:63]
	v_mfma_f32_16x16x32_bf16 v[56:59], v[206:209], v[154:157], v[56:59]
	s_waitcnt lgkmcnt(2)
	v_mfma_f32_16x16x32_bf16 v[52:55], v[182:185], v[170:173], v[52:55]
	v_mfma_f32_16x16x32_bf16 v[48:51], v[186:189], v[170:173], v[48:51]
	v_mfma_f32_16x16x32_bf16 v[44:47], v[202:205], v[170:173], v[44:47]
	v_mfma_f32_16x16x32_bf16 v[36:39], v[206:209], v[170:173], v[36:39]
	s_waitcnt lgkmcnt(1)
	v_mfma_f32_16x16x32_bf16 v[76:79], v[182:185], v[174:177], v[76:79]
	v_mfma_f32_16x16x32_bf16 v[72:75], v[186:189], v[174:177], v[72:75]
	v_mfma_f32_16x16x32_bf16 v[68:71], v[202:205], v[174:177], v[68:71]
	v_mfma_f32_16x16x32_bf16 v[40:43], v[206:209], v[174:177], v[40:43]
	s_waitcnt lgkmcnt(0)
	v_mfma_f32_16x16x32_bf16 v[84:87], v[182:185], v[178:181], v[84:87]
	v_mfma_f32_16x16x32_bf16 v[88:91], v[186:189], v[178:181], v[88:91]
	v_mfma_f32_16x16x32_bf16 v[92:95], v[202:205], v[178:181], v[92:95]
	v_mfma_f32_16x16x32_bf16 v[80:83], v[206:209], v[178:181], v[80:83]
	s_cmpk_eq_i32 s6, 0x780
	s_cbranch_scc0 .LBB0_250
	s_barrier
	s_waitcnt vmcnt(7)
	ds_write_b128 v148, v[0:3]
	s_waitcnt vmcnt(6)
	ds_write_b128 v148, v[4:7] offset:5120
	s_waitcnt vmcnt(5)
	ds_write_b128 v148, v[8:11] offset:10240
	s_waitcnt vmcnt(4)
	ds_write_b128 v148, v[12:15] offset:15360
	s_waitcnt vmcnt(3)
	ds_write_b128 v148, v[16:19] offset:20480
	s_waitcnt vmcnt(2)
	ds_write_b128 v148, v[20:23] offset:25600
	s_waitcnt vmcnt(1)
	ds_write_b128 v148, v[24:27] offset:30720
	s_waitcnt vmcnt(0)
	ds_write_b128 v148, v[28:31] offset:35840
	s_waitcnt lgkmcnt(0)
	s_barrier
	ds_read_b128 v[0:3], v149 offset:20480
	ds_read_b128 v[4:7], v134
	ds_read_b128 v[12:15], v149 offset:23040
	ds_read_b128 v[20:23], v149 offset:25600
	ds_read_b128 v[28:31], v149 offset:28160
	s_cmpk_lt_u32 s2, 0x800
	s_waitcnt lgkmcnt(3)
	v_mfma_f32_16x16x32_bf16 v[8:11], v[0:3], v[4:7], v[32:35]
	s_cselect_b64 s[6:7], -1, 0
	ds_read_b128 v[128:131], v149 offset:28224
	s_waitcnt lgkmcnt(3)
	v_mfma_f32_16x16x32_bf16 v[16:19], v[12:15], v[4:7], v[64:67]
	s_waitcnt lgkmcnt(2)
	v_mfma_f32_16x16x32_bf16 v[24:27], v[20:23], v[4:7], v[60:63]
	s_waitcnt lgkmcnt(1)
	v_mfma_f32_16x16x32_bf16 v[32:35], v[28:31], v[4:7], v[56:59]
	ds_read_b128 v[4:7], v134 offset:2560
	s_waitcnt lgkmcnt(0)
	v_mfma_f32_16x16x32_bf16 v[64:67], v[0:3], v[4:7], v[52:55]
	v_mfma_f32_16x16x32_bf16 v[116:119], v[12:15], v[4:7], v[48:51]
	v_mfma_f32_16x16x32_bf16 v[120:123], v[20:23], v[4:7], v[44:47]
	v_mfma_f32_16x16x32_bf16 v[36:39], v[28:31], v[4:7], v[36:39]
	ds_read_b128 v[4:7], v134 offset:5120
	s_waitcnt lgkmcnt(0)
	v_mfma_f32_16x16x32_bf16 v[124:127], v[28:31], v[4:7], v[40:43]
	s_nop 2
	ds_read_b128 v[40:43], v134 offset:7680
	v_mfma_f32_16x16x32_bf16 v[76:79], v[0:3], v[4:7], v[76:79]
	v_mfma_f32_16x16x32_bf16 v[72:75], v[12:15], v[4:7], v[72:75]
	v_mfma_f32_16x16x32_bf16 v[68:71], v[20:23], v[4:7], v[68:71]
	s_waitcnt lgkmcnt(0)
	v_mfma_f32_16x16x32_bf16 v[4:7], v[12:15], v[40:43], v[88:91]
	ds_read_b128 v[12:15], v149 offset:20544
	v_mfma_f32_16x16x32_bf16 v[84:87], v[0:3], v[40:43], v[84:87]
	s_nop 0
	ds_read_b128 v[88:91], v149 offset:23104
	v_mfma_f32_16x16x32_bf16 v[0:3], v[20:23], v[40:43], v[92:95]
	ds_read_b128 v[20:23], v134 offset:64
	s_nop 1
	ds_read_b128 v[92:95], v149 offset:25664
	s_waitcnt lgkmcnt(1)
	v_mfma_f32_16x16x32_bf16 v[56:59], v[12:15], v[20:23], v[8:11]
	s_nop 2
	ds_read_b128 v[8:11], v134 offset:2624
	v_mfma_f32_16x16x32_bf16 v[80:83], v[28:31], v[40:43], v[80:83]
	v_mfma_f32_16x16x32_bf16 v[48:51], v[128:131], v[20:23], v[32:35]
	s_waitcnt lgkmcnt(0)
	v_mfma_f32_16x16x32_bf16 v[40:43], v[12:15], v[8:11], v[64:67]
	v_mfma_f32_16x16x32_bf16 v[44:47], v[88:91], v[8:11], v[116:119]
	s_nop 1
	v_add_u32_e32 v64, s3, v133
	v_mfma_f32_16x16x32_bf16 v[32:35], v[92:95], v[8:11], v[120:123]
	v_mfma_f32_16x16x32_bf16 v[36:39], v[128:131], v[8:11], v[36:39]
	ds_read_b128 v[8:11], v134 offset:5184
	v_mfma_f32_16x16x32_bf16 v[52:55], v[92:95], v[20:23], v[24:27]
	s_waitcnt lgkmcnt(0)
	v_mfma_f32_16x16x32_bf16 v[24:27], v[12:15], v[8:11], v[76:79]
	v_mfma_f32_16x16x32_bf16 v[28:31], v[88:91], v[8:11], v[72:75]
	s_nop 2
	ds_read_b128 v[74:77], v134 offset:7744
	v_mfma_f32_16x16x32_bf16 v[60:63], v[88:91], v[20:23], v[16:19]
	v_or_b32_e32 v73, v64, v132
	v_cmp_lt_i32_e32 vcc, s22, v73
	s_and_b64 s[10:11], vcc, s[6:7]
	v_mfma_f32_16x16x32_bf16 v[16:19], v[92:95], v[8:11], v[68:71]
	v_mfma_f32_16x16x32_bf16 v[20:23], v[128:131], v[8:11], v[124:127]
	v_bfe_u32 v8, v64, 6, 6
	v_cvt_f32_ubyte0_e32 v65, v8
	v_mul_f32_e32 v66, v136, v65
	s_waitcnt lgkmcnt(0)
	v_mfma_f32_16x16x32_bf16 v[8:11], v[12:15], v[74:77], v[84:87]
	v_mul_f32_e32 v72, 0.15915494, v66
	v_mfma_f32_16x16x32_bf16 v[12:15], v[88:91], v[74:77], v[4:7]
	s_nop 2
	v_mul_f32_e32 v4, v137, v65
	v_mul_f32_e32 v5, v138, v65
	v_mul_f32_e32 v6, v139, v65
	v_mfma_f32_16x16x32_bf16 v[0:3], v[92:95], v[74:77], v[0:3]
	v_mul_f32_e32 v71, 0.15915494, v4
	v_mul_f32_e32 v70, 0.15915494, v5
	v_mul_f32_e32 v69, 0.15915494, v6
	v_mfma_f32_16x16x32_bf16 v[4:7], v[128:131], v[74:77], v[80:83]
	s_and_saveexec_b64 s[8:9], s[10:11]
	s_cbranch_execz .LBB0_253
	v_cos_f32_e32 v65, v70
	v_sin_f32_e32 v68, v70
	v_cos_f32_e32 v92, v69
	v_sin_f32_e32 v93, v69
	v_cos_f32_e32 v66, v72
	v_sin_f32_e32 v74, v72
	v_sin_f32_e32 v75, v71
	v_cos_f32_e32 v67, v71
	v_mul_f32_e32 v82, v68, v62
	v_mul_f32_e32 v86, v65, v62
	v_mov_b32_e32 v62, v59
	v_mul_f32_e32 v80, v65, v58
	v_mul_f32_e32 v84, v68, v58
	v_pk_mul_f32 v[58:59], v[92:93], v[62:63]
	v_mul_f32_e32 v90, v141, v50
	v_mul_f32_e32 v116, v140, v50
	v_mov_b32_e32 v81, v58
	v_mov_b32_e32 v83, v59
	v_mov_b32_e32 v58, v93
	v_mov_b32_e32 v59, v92
	v_mov_b32_e32 v50, v55
	v_pk_mul_f32 v[76:77], v[74:75], v[60:61]
	v_pk_mul_f32 v[60:61], v[66:67], v[60:61]
	v_pk_mul_f32 v[78:79], v[104:105], v[48:49]
	v_mul_f32_e32 v88, v140, v54
	v_mul_f32_e32 v94, v141, v54
	v_pk_mul_f32 v[58:59], v[58:59], v[62:63]
	v_pk_mul_f32 v[54:55], v[106:107], v[50:51]
	v_pk_mul_f32 v[50:51], v[108:109], v[50:51]
	v_pk_mul_f32 v[48:49], v[102:103], v[48:49]
	v_mov_b32_e32 v85, v58
	v_mov_b32_e32 v87, v59
	v_mov_b32_e32 v89, v54
	v_mov_b32_e32 v91, v55
	v_mov_b32_e32 v95, v50
	v_mov_b32_e32 v117, v51
	v_pk_fma_f32 v[66:67], v[66:67], v[56:57], v[76:77] neg_lo:[0,0,1] neg_hi:[0,0,1]
	v_pk_fma_f32 v[60:61], v[74:75], v[56:57], v[60:61]
	v_pk_fma_f32 v[74:75], v[102:103], v[52:53], v[78:79] neg_lo:[0,0,1] neg_hi:[0,0,1]
	v_pk_add_f32 v[58:59], v[80:81], v[82:83] neg_lo:[0,1] neg_hi:[0,1]
	v_pk_add_f32 v[62:63], v[84:85], v[86:87]
	v_pk_add_f32 v[54:55], v[88:89], v[90:91] neg_lo:[0,1] neg_hi:[0,1]
	v_pk_fma_f32 v[48:49], v[104:105], v[52:53], v[48:49]
	v_pk_add_f32 v[50:51], v[94:95], v[116:117]
	v_mov_b32_e32 v56, v66
	v_mov_b32_e32 v57, v67
	v_mov_b32_e32 v52, v74
	v_mov_b32_e32 v53, v75

.LBB0_296:
	s_and_b32 s2, s16, 7
	v_readlane_b32 s3, v254, 16
	s_lshl_b32 s2, s2, 8
	v_mov_b32_e32 v160, 0
	v_add_u32_e32 v0, s3, v227
	v_add_u32_e32 v0, s2, v0
	v_ashrrev_i32_e32 v1, 31, v0
	v_lshlrev_b64 v[0:1], 11, v[0:1]
	v_readlane_b32 s3, v254, 6
	v_lshl_add_u64 v[202:203], v[198:199], 0, v[0:1]
	s_mov_b64 s[6:7], 0
	v_add_u32_e32 v0, s3, v227
	v_add_u32_e32 v0, s2, v0
	v_ashrrev_i32_e32 v1, 31, v0
	v_lshlrev_b64 v[0:1], 11, v[0:1]
	v_readlane_b32 s3, v254, 7
	v_lshl_add_u64 v[204:205], v[198:199], 0, v[0:1]
	v_mov_b32_e32 v161, v160
	v_add_u32_e32 v0, s3, v227
	v_add_u32_e32 v0, s2, v0
	v_ashrrev_i32_e32 v1, 31, v0
	v_lshlrev_b64 v[0:1], 11, v[0:1]
	v_readlane_b32 s3, v254, 8
	v_lshl_add_u64 v[206:207], v[198:199], 0, v[0:1]
	v_mov_b32_e32 v162, v160
	v_add_u32_e32 v0, s3, v227
	v_add_u32_e32 v0, s2, v0
	v_ashrrev_i32_e32 v1, 31, v0
	v_lshlrev_b64 v[0:1], 11, v[0:1]
	v_readlane_b32 s3, v254, 13
	v_lshl_add_u64 v[208:209], v[198:199], 0, v[0:1]
	v_mov_b32_e32 v163, v160
	v_add_u32_e32 v0, s3, v227
	v_add_u32_e32 v0, s2, v0
	v_ashrrev_i32_e32 v1, 31, v0
	v_lshlrev_b64 v[0:1], 11, v[0:1]
	v_readlane_b32 s3, v254, 14
	v_lshl_add_u64 v[210:211], v[198:199], 0, v[0:1]
	v_mov_b32_e32 v164, v160
	v_add_u32_e32 v0, s3, v227
	v_add_u32_e32 v0, s2, v0
	v_ashrrev_i32_e32 v1, 31, v0
	v_lshlrev_b64 v[0:1], 11, v[0:1]
	v_readlane_b32 s3, v254, 15
	v_lshl_add_u64 v[212:213], v[198:199], 0, v[0:1]
	v_mov_b32_e32 v165, v160
	v_add_u32_e32 v0, s3, v227
	v_add_u32_e32 v0, s2, v0
	v_ashrrev_i32_e32 v1, 31, v0
	v_lshlrev_b64 v[0:1], 11, v[0:1]
	v_lshl_add_u64 v[214:215], v[198:199], 0, v[0:1]
	v_add_u32_e32 v0, s2, v241
	v_ashrrev_i32_e32 v1, 31, v0
	v_lshlrev_b64 v[0:1], 11, v[0:1]
	s_and_b32 s2, s15, 0xf80
	v_lshl_add_u64 v[216:217], v[198:199], 0, v[0:1]
	v_add_u32_e32 v0, s2, v227
	v_ashrrev_i32_e32 v1, 31, v0
	v_lshlrev_b64 v[0:1], 11, v[0:1]
	v_lshl_add_u64 v[218:219], v[200:201], 0, v[0:1]
	v_add_u32_e32 v0, s2, v242
	v_ashrrev_i32_e32 v1, 31, v0
	v_lshlrev_b64 v[0:1], 11, v[0:1]
	v_lshl_add_u64 v[220:221], v[200:201], 0, v[0:1]
	v_add_u32_e32 v0, s2, v243
	v_ashrrev_i32_e32 v1, 31, v0
	v_lshlrev_b64 v[0:1], 11, v[0:1]
	v_lshl_add_u64 v[222:223], v[200:201], 0, v[0:1]
	v_add_u32_e32 v0, s2, v244
	s_and_b32 s2, s17, 7
	v_ashrrev_i32_e32 v1, 31, v0
	s_or_b32 s2, s2, s33
	v_lshlrev_b64 v[0:1], 11, v[0:1]
	s_lshl_b32 s8, s2, 8
	v_lshl_add_u64 v[224:225], v[200:201], 0, v[0:1]
	v_add_u32_e32 v0, s8, v227
	v_ashrrev_i32_e32 v1, 31, v0
	v_lshlrev_b64 v[0:1], 11, v[0:1]
	v_lshl_add_u64 v[24:25], v[192:193], 0, v[0:1]
	s_mov_b32 s2, 0x10000
	v_add_co_u32_e32 v4, vcc, s2, v24
	s_mov_b32 s2, 0x20000
	s_nop 0
	v_addc_co_u32_e32 v5, vcc, 0, v25, vcc
	v_add_co_u32_e32 v8, vcc, s2, v24
	s_mov_b32 s2, 0x30000
	s_nop 0
	v_addc_co_u32_e32 v9, vcc, 0, v25, vcc
	v_add_co_u32_e32 v12, vcc, s2, v24
	s_mov_b32 s2, 0x40000
	s_nop 0
	v_addc_co_u32_e32 v13, vcc, 0, v25, vcc
	v_add_co_u32_e32 v16, vcc, s2, v24
	s_mov_b32 s2, 0x50000
	s_nop 0
	v_addc_co_u32_e32 v17, vcc, 0, v25, vcc
	s_lshl_b32 s3, s17, 4
	v_add_co_u32_e32 v20, vcc, s2, v24
	s_mov_b32 s2, 0x60000
	s_nop 0
	v_addc_co_u32_e32 v21, vcc, 0, v25, vcc
	s_and_b32 s10, s3, 0xf80
	v_add_co_u32_e32 v26, vcc, s2, v24
	v_add_u32_e32 v32, s10, v227
	s_nop 0
	v_addc_co_u32_e32 v27, vcc, 0, v25, vcc
	v_ashrrev_i32_e32 v33, 31, v32
	v_add_co_u32_e32 v28, vcc, 0x70000, v24
	v_lshlrev_b64 v[32:33], 11, v[32:33]
	s_nop 0
	v_addc_co_u32_e32 v29, vcc, 0, v25, vcc
	v_lshl_add_u64 v[40:41], v[194:195], 0, v[32:33]
	v_add_co_u32_e32 v36, vcc, 0x10000, v40
	global_load_dwordx4 v[0:3], v[24:25], off sc1
	s_nop 0
	global_load_dwordx4 v[4:7], v[4:5], off sc1
	v_addc_co_u32_e32 v37, vcc, 0, v41, vcc
	v_add_co_u32_e32 v42, vcc, 0x20000, v40
	global_load_dwordx4 v[8:11], v[8:9], off sc1
	s_nop 0
	global_load_dwordx4 v[12:15], v[12:13], off sc1
	v_addc_co_u32_e32 v43, vcc, 0, v41, vcc
	v_add_co_u32_e32 v44, vcc, 0x30000, v40
	global_load_dwordx4 v[16:19], v[16:17], off sc1
	s_nop 0
	global_load_dwordx4 v[20:23], v[20:21], off sc1
	v_addc_co_u32_e32 v45, vcc, 0, v41, vcc
	global_load_dwordx4 v[24:27], v[26:27], off sc1
	s_nop 0
	global_load_dwordx4 v[28:31], v[28:29], off sc1
	s_nop 0
	global_load_dwordx4 v[32:35], v[40:41], off sc1
	s_nop 0
	global_load_dwordx4 v[36:39], v[36:37], off sc1
	s_nop 0
	global_load_dwordx4 v[40:43], v[42:43], off sc1
	s_nop 0
	global_load_dwordx4 v[44:47], v[44:45], off sc1
	v_mov_b32_e32 v166, v160
	v_mov_b32_e32 v167, v160
	v_mov_b32_e32 v168, v160
	v_mov_b32_e32 v169, v160
	v_mov_b32_e32 v170, v160
	v_mov_b32_e32 v171, v160
	v_mov_b32_e32 v172, v160
	v_mov_b32_e32 v173, v160
	v_mov_b32_e32 v174, v160
	v_mov_b32_e32 v175, v160
	v_mov_b32_e32 v144, v160
	v_mov_b32_e32 v145, v160
	v_mov_b32_e32 v146, v160
	v_mov_b32_e32 v147, v160
	v_mov_b32_e32 v148, v160
	v_mov_b32_e32 v149, v160
	v_mov_b32_e32 v150, v160
	v_mov_b32_e32 v151, v160
	v_mov_b32_e32 v152, v160
	v_mov_b32_e32 v153, v160
	v_mov_b32_e32 v154, v160
	v_mov_b32_e32 v155, v160
	v_mov_b32_e32 v156, v160
	v_mov_b32_e32 v157, v160
	v_mov_b32_e32 v158, v160
	v_mov_b32_e32 v159, v160
	v_mov_b32_e32 v116, v160
	v_mov_b32_e32 v117, v160
	v_mov_b32_e32 v118, v160
	v_mov_b32_e32 v119, v160
	v_mov_b32_e32 v128, v160
	v_mov_b32_e32 v129, v160
	v_mov_b32_e32 v130, v160
	v_mov_b32_e32 v131, v160
	v_mov_b32_e32 v136, v160
	v_mov_b32_e32 v137, v160
	v_mov_b32_e32 v138, v160
	v_mov_b32_e32 v139, v160
	v_mov_b32_e32 v140, v160
	v_mov_b32_e32 v141, v160
	v_mov_b32_e32 v142, v160
	v_mov_b32_e32 v143, v160
	v_mov_b32_e32 v100, v160
	v_mov_b32_e32 v101, v160
	v_mov_b32_e32 v102, v160
	v_mov_b32_e32 v103, v160
	v_mov_b32_e32 v112, v160
	v_mov_b32_e32 v113, v160
	v_mov_b32_e32 v114, v160
	v_mov_b32_e32 v115, v160
	v_mov_b32_e32 v124, v160
	v_mov_b32_e32 v125, v160
	v_mov_b32_e32 v126, v160
	v_mov_b32_e32 v127, v160
	v_mov_b32_e32 v132, v160
	v_mov_b32_e32 v133, v160
	v_mov_b32_e32 v134, v160
	v_mov_b32_e32 v135, v160
	v_mov_b32_e32 v88, v160
	v_mov_b32_e32 v89, v160
	v_mov_b32_e32 v90, v160
	v_mov_b32_e32 v91, v160
	v_mov_b32_e32 v96, v160
	v_mov_b32_e32 v97, v160
	v_mov_b32_e32 v98, v160
	v_mov_b32_e32 v99, v160
	v_mov_b32_e32 v108, v160
	v_mov_b32_e32 v109, v160
	v_mov_b32_e32 v110, v160
	v_mov_b32_e32 v111, v160
	v_mov_b32_e32 v120, v160
	v_mov_b32_e32 v121, v160
	v_mov_b32_e32 v122, v160
	v_mov_b32_e32 v123, v160
	v_mov_b32_e32 v80, v160
	v_mov_b32_e32 v81, v160
	v_mov_b32_e32 v82, v160
	v_mov_b32_e32 v83, v160
	v_mov_b32_e32 v84, v160
	v_mov_b32_e32 v85, v160
	v_mov_b32_e32 v86, v160
	v_mov_b32_e32 v87, v160
	v_mov_b32_e32 v92, v160
	v_mov_b32_e32 v93, v160
	v_mov_b32_e32 v94, v160
	v_mov_b32_e32 v95, v160
	v_mov_b32_e32 v104, v160
	v_mov_b32_e32 v105, v160
	v_mov_b32_e32 v106, v160
	v_mov_b32_e32 v107, v160
	v_mov_b32_e32 v48, v160
	v_mov_b32_e32 v49, v160
	v_mov_b32_e32 v50, v160
	v_mov_b32_e32 v51, v160
	v_mov_b32_e32 v52, v160
	v_mov_b32_e32 v53, v160
	v_mov_b32_e32 v54, v160
	v_mov_b32_e32 v55, v160
	v_mov_b32_e32 v56, v160
	v_mov_b32_e32 v57, v160
	v_mov_b32_e32 v58, v160
	v_mov_b32_e32 v59, v160
	v_mov_b32_e32 v72, v160
	v_mov_b32_e32 v73, v160
	v_mov_b32_e32 v74, v160
	v_mov_b32_e32 v75, v160
	v_mov_b32_e32 v76, v160
	v_mov_b32_e32 v77, v160
	v_mov_b32_e32 v78, v160
	v_mov_b32_e32 v79, v160
	v_mov_b32_e32 v68, v160
	v_mov_b32_e32 v69, v160
	v_mov_b32_e32 v70, v160
	v_mov_b32_e32 v71, v160
	v_mov_b32_e32 v64, v160
	v_mov_b32_e32 v65, v160
	v_mov_b32_e32 v66, v160
	v_mov_b32_e32 v67, v160
	v_mov_b32_e32 v60, v160
	v_mov_b32_e32 v61, v160
	v_mov_b32_e32 v62, v160
	v_mov_b32_e32 v63, v160
	v_readfirstlane_b32 s76, v202
	v_readfirstlane_b32 s77, v203
	s_sub_u32 s76, s76, 0x100000
	s_subb_u32 s77, s77, 0
	v_readfirstlane_b32 s78, v218
	v_readfirstlane_b32 s79, v219
	s_sub_u32 s78, s78, 0x100000
	s_subb_u32 s79, s79, 0
	v_subrev_u32_e32 v202, s76, v202
	v_subrev_u32_e32 v204, s76, v204
	v_subrev_u32_e32 v206, s76, v206
	v_subrev_u32_e32 v208, s76, v208
	v_subrev_u32_e32 v210, s76, v210
	v_subrev_u32_e32 v212, s76, v212
	v_subrev_u32_e32 v214, s76, v214
	v_subrev_u32_e32 v216, s76, v216
	v_subrev_u32_e32 v218, s78, v218
	v_subrev_u32_e32 v220, s78, v220
	v_subrev_u32_e32 v222, s78, v222
	v_subrev_u32_e32 v224, s78, v224
.LBB0_297:
	s_barrier
	s_waitcnt vmcnt(11)
	ds_write_b128 v245, v[0:3]
	s_waitcnt vmcnt(10)
	ds_write_b128 v245, v[4:7] offset:5120
	s_waitcnt vmcnt(9)
	ds_write_b128 v245, v[8:11] offset:10240
	s_waitcnt vmcnt(8)
	ds_write_b128 v245, v[12:15] offset:15360
	s_waitcnt vmcnt(7)
	ds_write_b128 v245, v[16:19] offset:20480
	s_waitcnt vmcnt(6)
	ds_write_b128 v245, v[20:23] offset:25600
	s_waitcnt vmcnt(5)
	ds_write_b128 v245, v[24:27] offset:30720
	s_waitcnt vmcnt(4)
	ds_write_b128 v245, v[28:31] offset:35840
	s_waitcnt vmcnt(3)
	ds_write_b128 v245, v[32:35] offset:40960
	s_waitcnt vmcnt(2)
	ds_write_b128 v245, v[36:39] offset:46080
	s_waitcnt vmcnt(1)
	ds_write_b128 v245, v[40:43] offset:51200
	s_waitcnt vmcnt(0)
	ds_write_b128 v245, v[44:47] offset:56320
	s_add_u32 s80, s76, s6
	s_addc_u32 s81, s77, s7
	s_add_u32 s82, s78, s6
	s_addc_u32 s83, s79, s7
	s_waitcnt lgkmcnt(0)
	s_barrier
	global_load_dwordx4 v[0:3], v202, s[80:81] sc1
	global_load_dwordx4 v[4:7], v204, s[80:81] sc1
	global_load_dwordx4 v[8:11], v206, s[80:81] sc1
	global_load_dwordx4 v[12:15], v208, s[80:81] sc1
	global_load_dwordx4 v[16:19], v210, s[80:81] sc1
	global_load_dwordx4 v[20:23], v212, s[80:81] sc1
	global_load_dwordx4 v[24:27], v214, s[80:81] sc1
	global_load_dwordx4 v[28:31], v216, s[80:81] sc1
	global_load_dwordx4 v[32:35], v218, s[82:83] sc1
	global_load_dwordx4 v[36:39], v220, s[82:83] sc1
	global_load_dwordx4 v[40:43], v222, s[82:83] sc1
	global_load_dwordx4 v[44:47], v224, s[82:83] sc1
	ds_read_b128 v[176:179], v246 offset:40960
	ds_read_b128 v[184:187], v246 offset:43520
	ds_read_b128 v[188:191], v246 offset:46080
	ds_read_b128 v[230:233], v246 offset:48640
	ds_read_b128 v[180:183], v238
	ds_read_b128 v[248:251], v238 offset:2560
	s_add_u32 s6, s6, 0x80
	s_addc_u32 s7, s7, 0
	s_waitcnt lgkmcnt(1)
	v_mfma_f32_16x16x32_bf16 v[60:63], v[176:179], v[180:183], v[60:63]
	v_mfma_f32_16x16x32_bf16 v[64:67], v[184:187], v[180:183], v[64:67]
	v_mfma_f32_16x16x32_bf16 v[68:71], v[188:191], v[180:183], v[68:71]
	v_mfma_f32_16x16x32_bf16 v[76:79], v[230:233], v[180:183], v[76:79]
	ds_read_b128 v[180:183], v238 offset:5120
	s_waitcnt lgkmcnt(1)
	v_mfma_f32_16x16x32_bf16 v[72:75], v[176:179], v[248:251], v[72:75]
	v_mfma_f32_16x16x32_bf16 v[56:59], v[184:187], v[248:251], v[56:59]
	v_mfma_f32_16x16x32_bf16 v[52:55], v[188:191], v[248:251], v[52:55]
	v_mfma_f32_16x16x32_bf16 v[48:51], v[230:233], v[248:251], v[48:51]
	ds_read_b128 v[248:251], v238 offset:7680
	s_waitcnt lgkmcnt(1)
	v_mfma_f32_16x16x32_bf16 v[104:107], v[176:179], v[180:183], v[104:107]
	v_mfma_f32_16x16x32_bf16 v[92:95], v[184:187], v[180:183], v[92:95]
	v_mfma_f32_16x16x32_bf16 v[84:87], v[188:191], v[180:183], v[84:87]
	v_mfma_f32_16x16x32_bf16 v[80:83], v[230:233], v[180:183], v[80:83]
	ds_read_b128 v[180:183], v238 offset:10240
	s_waitcnt lgkmcnt(1)
	v_mfma_f32_16x16x32_bf16 v[120:123], v[176:179], v[248:251], v[120:123]
	v_mfma_f32_16x16x32_bf16 v[108:111], v[184:187], v[248:251], v[108:111]
	v_mfma_f32_16x16x32_bf16 v[96:99], v[188:191], v[248:251], v[96:99]
	v_mfma_f32_16x16x32_bf16 v[88:91], v[230:233], v[248:251], v[88:91]
	ds_read_b128 v[248:251], v238 offset:12800
	s_waitcnt lgkmcnt(1)
	v_mfma_f32_16x16x32_bf16 v[132:135], v[176:179], v[180:183], v[132:135]
	v_mfma_f32_16x16x32_bf16 v[124:127], v[184:187], v[180:183], v[124:127]
	v_mfma_f32_16x16x32_bf16 v[112:115], v[188:191], v[180:183], v[112:115]
	v_mfma_f32_16x16x32_bf16 v[100:103], v[230:233], v[180:183], v[100:103]
	ds_read_b128 v[180:183], v238 offset:15360
	s_waitcnt lgkmcnt(1)
	v_mfma_f32_16x16x32_bf16 v[140:143], v[176:179], v[248:251], v[140:143]
	v_mfma_f32_16x16x32_bf16 v[136:139], v[184:187], v[248:251], v[136:139]
	v_mfma_f32_16x16x32_bf16 v[128:131], v[188:191], v[248:251], v[128:131]
	v_mfma_f32_16x16x32_bf16 v[116:119], v[230:233], v[248:251], v[116:119]
	ds_read_b128 v[248:251], v247
	s_waitcnt lgkmcnt(1)
	v_mfma_f32_16x16x32_bf16 v[156:159], v[176:179], v[180:183], v[156:159]
	v_mfma_f32_16x16x32_bf16 v[152:155], v[184:187], v[180:183], v[152:155]
	v_mfma_f32_16x16x32_bf16 v[148:151], v[188:191], v[180:183], v[148:151]
	v_mfma_f32_16x16x32_bf16 v[144:147], v[230:233], v[180:183], v[144:147]
	ds_read_b128 v[180:183], v238 offset:64
	s_waitcnt lgkmcnt(1)
	v_mfma_f32_16x16x32_bf16 v[172:175], v[176:179], v[248:251], v[172:175]
	ds_read_b128 v[176:179], v246 offset:41024
	v_mfma_f32_16x16x32_bf16 v[168:171], v[184:187], v[248:251], v[168:171]
	ds_read_b128 v[184:187], v246 offset:43584
	v_mfma_f32_16x16x32_bf16 v[164:167], v[188:191], v[248:251], v[164:167]
	ds_read_b128 v[188:191], v246 offset:46144
	v_mfma_f32_16x16x32_bf16 v[160:163], v[230:233], v[248:251], v[160:163]
	ds_read_b128 v[230:233], v246 offset:48704
	ds_read_b128 v[248:251], v238 offset:2624
	s_waitcnt lgkmcnt(1)
	v_mfma_f32_16x16x32_bf16 v[60:63], v[176:179], v[180:183], v[60:63]
	v_mfma_f32_16x16x32_bf16 v[64:67], v[184:187], v[180:183], v[64:67]
	v_mfma_f32_16x16x32_bf16 v[68:71], v[188:191], v[180:183], v[68:71]
	v_mfma_f32_16x16x32_bf16 v[76:79], v[230:233], v[180:183], v[76:79]
	ds_read_b128 v[180:183], v238 offset:5184
	s_waitcnt lgkmcnt(1)
	v_mfma_f32_16x16x32_bf16 v[72:75], v[176:179], v[248:251], v[72:75]
	v_mfma_f32_16x16x32_bf16 v[56:59], v[184:187], v[248:251], v[56:59]
	v_mfma_f32_16x16x32_bf16 v[52:55], v[188:191], v[248:251], v[52:55]
	v_mfma_f32_16x16x32_bf16 v[48:51], v[230:233], v[248:251], v[48:51]
	ds_read_b128 v[248:251], v238 offset:7744
	s_waitcnt lgkmcnt(1)
	v_mfma_f32_16x16x32_bf16 v[104:107], v[176:179], v[180:183], v[104:107]
	v_mfma_f32_16x16x32_bf16 v[92:95], v[184:187], v[180:183], v[92:95]
	v_mfma_f32_16x16x32_bf16 v[84:87], v[188:191], v[180:183], v[84:87]
	v_mfma_f32_16x16x32_bf16 v[80:83], v[230:233], v[180:183], v[80:83]
	ds_read_b128 v[180:183], v238 offset:10304
	s_waitcnt lgkmcnt(1)
	v_mfma_f32_16x16x32_bf16 v[120:123], v[176:179], v[248:251], v[120:123]
	v_mfma_f32_16x16x32_bf16 v[108:111], v[184:187], v[248:251], v[108:111]
	v_mfma_f32_16x16x32_bf16 v[96:99], v[188:191], v[248:251], v[96:99]
	v_mfma_f32_16x16x32_bf16 v[88:91], v[230:233], v[248:251], v[88:91]
	ds_read_b128 v[248:251], v238 offset:12864
	s_waitcnt lgkmcnt(1)
	v_mfma_f32_16x16x32_bf16 v[132:135], v[176:179], v[180:183], v[132:135]
	v_mfma_f32_16x16x32_bf16 v[124:127], v[184:187], v[180:183], v[124:127]
	v_mfma_f32_16x16x32_bf16 v[112:115], v[188:191], v[180:183], v[112:115]
	v_mfma_f32_16x16x32_bf16 v[100:103], v[230:233], v[180:183], v[100:103]
	ds_read_b128 v[180:183], v238 offset:15424
	s_waitcnt lgkmcnt(1)
	v_mfma_f32_16x16x32_bf16 v[140:143], v[176:179], v[248:251], v[140:143]
	v_mfma_f32_16x16x32_bf16 v[136:139], v[184:187], v[248:251], v[136:139]
	v_mfma_f32_16x16x32_bf16 v[128:131], v[188:191], v[248:251], v[128:131]
	v_mfma_f32_16x16x32_bf16 v[116:119], v[230:233], v[248:251], v[116:119]
	ds_read_b128 v[248:251], v247 offset:64
	s_waitcnt lgkmcnt(1)
	v_mfma_f32_16x16x32_bf16 v[156:159], v[176:179], v[180:183], v[156:159]
	v_mfma_f32_16x16x32_bf16 v[152:155], v[184:187], v[180:183], v[152:155]
	v_mfma_f32_16x16x32_bf16 v[148:151], v[188:191], v[180:183], v[148:151]
	v_mfma_f32_16x16x32_bf16 v[144:147], v[230:233], v[180:183], v[144:147]
	s_waitcnt lgkmcnt(0)
	v_mfma_f32_16x16x32_bf16 v[172:175], v[176:179], v[248:251], v[172:175]
	v_mfma_f32_16x16x32_bf16 v[168:171], v[184:187], v[248:251], v[168:171]
	v_mfma_f32_16x16x32_bf16 v[164:167], v[188:191], v[248:251], v[164:167]
	v_mfma_f32_16x16x32_bf16 v[160:163], v[230:233], v[248:251], v[160:163]
	s_cmpk_eq_i32 s6, 0x780
	s_cbranch_scc0 .LBB0_297
	s_barrier
	s_waitcnt vmcnt(11)
	ds_write_b128 v245, v[0:3]
	s_waitcnt vmcnt(10)
	ds_write_b128 v245, v[4:7] offset:5120
	s_waitcnt vmcnt(9)
	ds_write_b128 v245, v[8:11] offset:10240
	s_waitcnt vmcnt(8)
	ds_write_b128 v245, v[12:15] offset:15360
	s_waitcnt vmcnt(7)
	ds_write_b128 v245, v[16:19] offset:20480
	s_waitcnt vmcnt(6)
	ds_write_b128 v245, v[20:23] offset:25600
	s_waitcnt vmcnt(5)
	ds_write_b128 v245, v[24:27] offset:30720
	s_waitcnt vmcnt(4)
	ds_write_b128 v245, v[28:31] offset:35840
	s_waitcnt vmcnt(3)
	ds_write_b128 v245, v[32:35] offset:40960
	s_waitcnt vmcnt(2)
	ds_write_b128 v245, v[36:39] offset:46080
	s_waitcnt vmcnt(1)
	ds_write_b128 v245, v[40:43] offset:51200
	s_waitcnt vmcnt(0)
	ds_write_b128 v245, v[44:47] offset:56320
	s_waitcnt lgkmcnt(0)
	s_barrier
	ds_read_b128 v[176:179], v246 offset:40960
	ds_read_b128 v[180:183], v246 offset:43520
	ds_read_b128 v[184:187], v246 offset:46080
	ds_read_b128 v[188:191], v246 offset:48640
	ds_read_b128 v[0:3], v238 offset:2560
	ds_read_b128 v[4:7], v238 offset:5120
	ds_read_b128 v[8:11], v238
	s_add_i32 s2, s10, 0xfffffe00
	s_cmpk_lt_u32 s2, 0x400
	s_waitcnt lgkmcnt(2)
	v_mfma_f32_16x16x32_bf16 v[218:221], v[176:179], v[0:3], v[72:75]
	v_or_b32_e32 v196, s10, v240
	ds_read_b128 v[20:23], v238 offset:15360
	s_waitcnt lgkmcnt(1)
	v_mfma_f32_16x16x32_bf16 v[202:205], v[176:179], v[8:11], v[60:63]
	v_mfma_f32_16x16x32_bf16 v[206:209], v[180:183], v[8:11], v[64:67]
	v_mfma_f32_16x16x32_bf16 v[210:213], v[184:187], v[8:11], v[68:71]
	v_mfma_f32_16x16x32_bf16 v[214:217], v[188:191], v[8:11], v[76:79]
	ds_read_b128 v[8:11], v238 offset:7680
	v_mfma_f32_16x16x32_bf16 v[222:225], v[180:183], v[0:3], v[56:59]
	v_mfma_f32_16x16x32_bf16 v[248:251], v[184:187], v[0:3], v[52:55]
	v_mfma_f32_16x16x32_bf16 v[230:233], v[188:191], v[0:3], v[48:51]
	ds_read_b128 v[0:3], v238 offset:10240
	v_mfma_f32_16x16x32_bf16 v[64:67], v[176:179], v[4:7], v[104:107]
	v_mfma_f32_16x16x32_bf16 v[68:71], v[180:183], v[4:7], v[92:95]
	v_mfma_f32_16x16x32_bf16 v[72:75], v[184:187], v[4:7], v[84:87]
	v_mfma_f32_16x16x32_bf16 v[76:79], v[188:191], v[4:7], v[80:83]
	ds_read_b128 v[4:7], v238 offset:12800
	s_nop 1
	ds_read_b128 v[80:83], v247
	s_waitcnt lgkmcnt(3)
	v_mfma_f32_16x16x32_bf16 v[48:51], v[176:179], v[8:11], v[120:123]
	v_mfma_f32_16x16x32_bf16 v[52:55], v[180:183], v[8:11], v[108:111]
	v_mfma_f32_16x16x32_bf16 v[56:59], v[184:187], v[8:11], v[96:99]
	v_mfma_f32_16x16x32_bf16 v[60:63], v[188:191], v[8:11], v[88:91]
	s_waitcnt lgkmcnt(2)
	v_mfma_f32_16x16x32_bf16 v[32:35], v[176:179], v[0:3], v[132:135]
	v_mfma_f32_16x16x32_bf16 v[36:39], v[180:183], v[0:3], v[124:127]
	v_mfma_f32_16x16x32_bf16 v[40:43], v[184:187], v[0:3], v[112:115]
	v_mfma_f32_16x16x32_bf16 v[44:47], v[188:191], v[0:3], v[100:103]
	s_waitcnt lgkmcnt(1)
	v_mfma_f32_16x16x32_bf16 v[0:3], v[184:187], v[4:7], v[128:131]
	v_mfma_f32_16x16x32_bf16 v[8:11], v[176:179], v[20:23], v[156:159]
	v_mfma_f32_16x16x32_bf16 v[12:15], v[180:183], v[20:23], v[152:155]
	v_mfma_f32_16x16x32_bf16 v[16:19], v[184:187], v[20:23], v[148:151]
	v_mfma_f32_16x16x32_bf16 v[20:23], v[188:191], v[20:23], v[144:147]
	s_waitcnt lgkmcnt(0)
	v_mfma_f32_16x16x32_bf16 v[120:123], v[176:179], v[80:83], v[172:175]
	v_mfma_f32_16x16x32_bf16 v[124:127], v[180:183], v[80:83], v[168:171]
	v_mfma_f32_16x16x32_bf16 v[128:131], v[184:187], v[80:83], v[164:167]
	v_mfma_f32_16x16x32_bf16 v[132:135], v[188:191], v[80:83], v[160:163]
	ds_read_b128 v[144:147], v246 offset:41024
	ds_read_b128 v[148:151], v246 offset:43584
	ds_read_b128 v[152:155], v246 offset:46144
	ds_read_b128 v[156:159], v246 offset:48704
	ds_read_b128 v[80:83], v238 offset:2624
	ds_read_b128 v[84:87], v238 offset:5184
	ds_read_b128 v[88:91], v238 offset:64
	ds_read_b128 v[160:163], v238 offset:7744
	ds_read_b128 v[164:167], v238 offset:10304
	v_mfma_f32_16x16x32_bf16 v[24:27], v[176:179], v[4:7], v[140:143]
	ds_read_b128 v[168:171], v238 offset:12864
	v_mfma_f32_16x16x32_bf16 v[28:31], v[180:183], v[4:7], v[136:139]
	v_mfma_f32_16x16x32_bf16 v[4:7], v[188:191], v[4:7], v[116:119]
	s_waitcnt lgkmcnt(3)
	v_mfma_f32_16x16x32_bf16 v[140:143], v[144:147], v[88:91], v[202:205]
	v_mfma_f32_16x16x32_bf16 v[136:139], v[148:151], v[88:91], v[206:209]
	v_mfma_f32_16x16x32_bf16 v[116:119], v[152:155], v[88:91], v[210:213]
	v_mfma_f32_16x16x32_bf16 v[104:107], v[156:159], v[88:91], v[214:217]
	v_mfma_f32_16x16x32_bf16 v[108:111], v[144:147], v[80:83], v[218:221]
	v_mfma_f32_16x16x32_bf16 v[112:115], v[148:151], v[80:83], v[222:225]
	v_mfma_f32_16x16x32_bf16 v[96:99], v[152:155], v[80:83], v[248:251]
	v_mfma_f32_16x16x32_bf16 v[100:103], v[156:159], v[80:83], v[230:233]
	v_mfma_f32_16x16x32_bf16 v[88:91], v[144:147], v[84:87], v[64:67]
	v_mfma_f32_16x16x32_bf16 v[92:95], v[148:151], v[84:87], v[68:71]
	v_mfma_f32_16x16x32_bf16 v[80:83], v[152:155], v[84:87], v[72:75]
	v_mfma_f32_16x16x32_bf16 v[84:87], v[156:159], v[84:87], v[76:79]
	s_waitcnt lgkmcnt(2)
	v_mfma_f32_16x16x32_bf16 v[72:75], v[144:147], v[160:163], v[48:51]
	v_mfma_f32_16x16x32_bf16 v[76:79], v[148:151], v[160:163], v[52:55]
	v_mfma_f32_16x16x32_bf16 v[64:67], v[152:155], v[160:163], v[56:59]
	v_mfma_f32_16x16x32_bf16 v[68:71], v[156:159], v[160:163], v[60:63]
	ds_read_b128 v[160:163], v238 offset:15424
	s_waitcnt lgkmcnt(2)
	v_mfma_f32_16x16x32_bf16 v[56:59], v[144:147], v[164:167], v[32:35]
	v_mfma_f32_16x16x32_bf16 v[60:63], v[148:151], v[164:167], v[36:39]
	v_mfma_f32_16x16x32_bf16 v[40:43], v[152:155], v[164:167], v[40:43]
	v_mfma_f32_16x16x32_bf16 v[44:47], v[156:159], v[164:167], v[44:47]
	ds_read_b128 v[164:167], v247 offset:64
	s_waitcnt lgkmcnt(2)
	v_mfma_f32_16x16x32_bf16 v[48:51], v[144:147], v[168:171], v[24:27]
	s_waitcnt lgkmcnt(1)
	v_mfma_f32_16x16x32_bf16 v[24:27], v[144:147], v[160:163], v[8:11]
	s_waitcnt lgkmcnt(0)
	v_mfma_f32_16x16x32_bf16 v[8:11], v[144:147], v[164:167], v[120:123]
	s_nop 2
	v_add_u32_e32 v120, s8, v239
	v_mfma_f32_16x16x32_bf16 v[52:55], v[148:151], v[168:171], v[28:31]
	s_cselect_b64 s[8:9], -1, 0
	s_cmpk_lt_u32 s10, 0x400
	s_cselect_b64 s[6:7], -1, 0
	v_mfma_f32_16x16x32_bf16 v[28:31], v[148:151], v[160:163], v[12:15]
	v_mfma_f32_16x16x32_bf16 v[12:15], v[148:151], v[164:167], v[124:127]
	s_nop 2
	v_or_b32_e32 v125, v120, v226
	v_lshlrev_b32_e32 v120, 1, v120
	v_and_b32_e32 v120, 0xfffffe00, v120
	v_add_u32_e32 v124, s14, v120
	v_mov_b64_e32 v[120:121], s[44:45]
	v_mad_i64_i32 v[120:121], s[2:3], v125, s70, v[120:121]
	s_movk_i32 s2, 0x2000
	s_nop 0
	v_cmp_gt_i32_e32 vcc, s2, v125
	s_movk_i32 s2, 0x8f
	v_and_or_b32 v122, v125, s2, v124
	v_mfma_f32_16x16x32_bf16 v[32:35], v[152:155], v[168:171], v[0:3]
	v_ashrrev_i32_e32 v123, 31, v122
	v_lshlrev_b64 v[126:127], 11, v[122:123]
	v_lshlrev_b32_e32 v122, 1, v196
	v_mfma_f32_16x16x32_bf16 v[36:39], v[156:159], v[168:171], v[4:7]
	v_mov_b32_e32 v123, v197
	v_lshl_add_u64 v[122:123], v[120:121], 0, v[122:123]
	v_lshl_add_u64 v[120:121], s[88:89], 0, v[126:127]
	v_mfma_f32_16x16x32_bf16 v[16:19], v[152:155], v[160:163], v[16:19]
	s_and_b64 s[10:11], vcc, s[8:9]
	v_lshl_add_u64 v[120:121], v[196:197], 2, v[120:121]
	v_mfma_f32_16x16x32_bf16 v[20:23], v[156:159], v[160:163], v[20:23]
	v_mfma_f32_16x16x32_bf16 v[0:3], v[152:155], v[164:167], v[128:131]
	v_mfma_f32_16x16x32_bf16 v[4:7], v[156:159], v[164:167], v[132:135]
	s_nop 1
	v_cvt_pk_bf16_f32 v128, v140, v141
	v_cvt_pk_bf16_f32 v129, v142, v143
	global_store_dwordx2 v[122:123], v[128:129], off
	s_and_saveexec_b64 s[12:13], s[10:11]
	s_cbranch_execz .LBB0_300
	s_and_b64 s[2:3], s[6:7], exec
	s_mov_b32 s2, 0x3fff800
	s_cselect_b32 s50, s2, 0x5fff000
	v_lshl_add_u64 v[126:127], v[120:121], 0, s[50:51]
	global_store_dwordx4 v[126:127], v[140:143], off

.LBB0_426:
	s_mov_b32 s32, 0x3e38aa3b
	s_barrier
	s_waitcnt vmcnt(0)
	ds_write_b128 v238, v[24:27]
	ds_write_b128 v239, v[28:31]
	s_add_i32 s27, s28, 1
	ds_write_b128 v240, v[40:43]
	s_cmp_ge_u32 s27, s3
	ds_write_b128 v241, v[44:47]
	ds_write_b128 v147, v[32:35] offset:18432
	ds_write_b128 v148, v[36:39] offset:18432
	ds_write_b128 v149, v[16:19] offset:18432
	ds_write_b128 v150, v[20:23] offset:18432
	s_waitcnt lgkmcnt(0)
	s_barrier
	ds_read_b128 v[198:201], v153
	ds_read_b128 v[202:205], v153 offset:4608
	ds_read_b128 v[206:209], v153 offset:9216
	ds_read_b128 v[210:213], v153 offset:13824
	ds_read_b128 v[216:219], v153 offset:64
	ds_read_b128 v[220:223], v153 offset:4672
	ds_read_b128 v[224:227], v153 offset:9280
	ds_read_b128 v[230:233], v153 offset:13888
	s_cbranch_scc1 .LBB0_430
	s_cmp_lt_u32 s27, s2
	s_mov_b32 s29, s27
	s_mov_b64 s[18:19], s[10:11]
	s_mov_b64 s[22:23], s[6:7]
	s_mov_b64 s[20:21], s[8:9]
	s_cbranch_scc1 .LBB0_429
	s_add_i32 s29, s25, s28
	s_mov_b64 s[18:19], 0xc00
	s_mov_b64 s[22:23], s[14:15]
	s_mov_b64 s[20:21], s[16:17]

.LBB0_430:
	s_waitcnt lgkmcnt(7)
	v_mfma_f32_16x16x32_bf16 v[174:177], v[198:201], v[0:3], 0
	ds_read_b128 v[198:201], v153 offset:128
	s_waitcnt lgkmcnt(7)
	v_mfma_f32_16x16x32_bf16 v[160:163], v[202:205], v[0:3], 0
	ds_read_b128 v[202:205], v153 offset:4736
	s_waitcnt lgkmcnt(7)
	v_mfma_f32_16x16x32_bf16 v[166:169], v[206:209], v[0:3], 0
	ds_read_b128 v[206:209], v153 offset:9344
	s_waitcnt lgkmcnt(7)
	v_mfma_f32_16x16x32_bf16 v[170:173], v[210:213], v[0:3], 0
	ds_read_b128 v[210:213], v153 offset:13952
	s_waitcnt lgkmcnt(7)
	v_mfma_f32_16x16x32_bf16 v[174:177], v[216:219], v[4:7], v[174:177]
	ds_read_b128 v[216:219], v153 offset:192
	s_waitcnt lgkmcnt(7)
	v_mfma_f32_16x16x32_bf16 v[160:163], v[220:223], v[4:7], v[160:163]
	ds_read_b128 v[220:223], v153 offset:4800
	s_waitcnt lgkmcnt(7)
	v_mfma_f32_16x16x32_bf16 v[166:169], v[224:227], v[4:7], v[166:169]
	ds_read_b128 v[224:227], v153 offset:9408
	s_waitcnt lgkmcnt(7)
	v_mfma_f32_16x16x32_bf16 v[170:173], v[230:233], v[4:7], v[170:173]
	ds_read_b128 v[230:233], v153 offset:14016
	s_waitcnt lgkmcnt(7)
	v_mfma_f32_16x16x32_bf16 v[112:115], v[198:201], v[8:11], 0
	s_waitcnt lgkmcnt(6)
	v_mfma_f32_16x16x32_bf16 v[116:119], v[202:205], v[8:11], 0
	s_waitcnt lgkmcnt(5)
	v_mfma_f32_16x16x32_bf16 v[186:189], v[206:209], v[8:11], 0
	s_waitcnt lgkmcnt(4)
	v_mfma_f32_16x16x32_bf16 v[182:185], v[210:213], v[8:11], 0
	s_waitcnt lgkmcnt(3)
	v_mfma_f32_16x16x32_bf16 v[112:115], v[216:219], v[12:15], v[112:115]
	s_waitcnt lgkmcnt(2)
	v_mfma_f32_16x16x32_bf16 v[116:119], v[220:223], v[12:15], v[116:119]
	s_waitcnt lgkmcnt(1)
	v_mfma_f32_16x16x32_bf16 v[186:189], v[224:227], v[12:15], v[186:189]
	s_waitcnt lgkmcnt(0)
	v_mfma_f32_16x16x32_bf16 v[182:185], v[230:233], v[12:15], v[182:185]
	v_max3_f32 v194, v174, s30, v175
	v_max3_f32 v194, v194, v176, v177
	v_max3_f32 v194, v194, v160, v161
	v_max3_f32 v194, v194, v162, v163
	v_max3_f32 v194, v194, v166, v167
	v_max3_f32 v194, v194, v168, v169
	v_max3_f32 v194, v194, v170, v171
	v_max3_f32 v194, v194, v172, v173
	v_mov_b32_e32 v195, v194
	s_nop 1
	v_permlane16_swap_b32_e32 v194, v195
	v_max_f32_e32 v194, v194, v195
	v_mov_b32_e32 v195, v194
	s_nop 1
	v_permlane32_swap_b32_e32 v194, v195
	v_max_f32_e32 v194, v194, v195
	v_mul_f32_e32 v194, 0x3e38aa3b, v194
	v_max_f32_e32 v194, v155, v194
	v_pk_fma_f32 v[174:175], v[174:175], s[32:33], v[194:195] op_sel_hi:[1,0,0] neg_lo:[0,0,1] neg_hi:[0,0,1]
	v_pk_fma_f32 v[176:177], v[176:177], s[32:33], v[194:195] op_sel_hi:[1,0,0] neg_lo:[0,0,1] neg_hi:[0,0,1]
	v_pk_fma_f32 v[160:161], v[160:161], s[32:33], v[194:195] op_sel_hi:[1,0,0] neg_lo:[0,0,1] neg_hi:[0,0,1]
	v_pk_fma_f32 v[162:163], v[162:163], s[32:33], v[194:195] op_sel_hi:[1,0,0] neg_lo:[0,0,1] neg_hi:[0,0,1]
	v_pk_fma_f32 v[166:167], v[166:167], s[32:33], v[194:195] op_sel_hi:[1,0,0] neg_lo:[0,0,1] neg_hi:[0,0,1]
	v_pk_fma_f32 v[168:169], v[168:169], s[32:33], v[194:195] op_sel_hi:[1,0,0] neg_lo:[0,0,1] neg_hi:[0,0,1]
	v_pk_fma_f32 v[170:171], v[170:171], s[32:33], v[194:195] op_sel_hi:[1,0,0] neg_lo:[0,0,1] neg_hi:[0,0,1]
	v_pk_fma_f32 v[172:173], v[172:173], s[32:33], v[194:195] op_sel_hi:[1,0,0] neg_lo:[0,0,1] neg_hi:[0,0,1]
	v_cmp_gt_f32_e32 vcc, v194, v155
	s_cbranch_vccz .LBB0_432
	v_sub_f32_e32 v155, v155, v194
	v_exp_f32_e32 v215, v155
	v_mov_b32_e32 v155, v194
	v_mul_f32_e32 v131, v131, v215
	v_pk_mul_f32 v[98:99], v[98:99], v[214:215] op_sel:[0,1] op_sel_hi:[1,1]
	v_pk_mul_f32 v[96:97], v[96:97], v[214:215] op_sel:[0,1] op_sel_hi:[1,1]
	v_pk_mul_f32 v[102:103], v[102:103], v[214:215] op_sel:[0,1] op_sel_hi:[1,1]
	v_pk_mul_f32 v[100:101], v[100:101], v[214:215] op_sel:[0,1] op_sel_hi:[1,1]
	v_pk_mul_f32 v[70:71], v[70:71], v[214:215] op_sel:[0,1] op_sel_hi:[1,1]
	v_pk_mul_f32 v[68:69], v[68:69], v[214:215] op_sel:[0,1] op_sel_hi:[1,1]
	v_pk_mul_f32 v[54:55], v[54:55], v[214:215] op_sel:[0,1] op_sel_hi:[1,1]
	v_pk_mul_f32 v[52:53], v[52:53], v[214:215] op_sel:[0,1] op_sel_hi:[1,1]
	v_pk_mul_f32 v[82:83], v[82:83], v[214:215] op_sel:[0,1] op_sel_hi:[1,1]
	v_pk_mul_f32 v[80:81], v[80:81], v[214:215] op_sel:[0,1] op_sel_hi:[1,1]
	v_pk_mul_f32 v[86:87], v[86:87], v[214:215] op_sel:[0,1] op_sel_hi:[1,1]
	v_pk_mul_f32 v[84:85], v[84:85], v[214:215] op_sel:[0,1] op_sel_hi:[1,1]
	v_pk_mul_f32 v[78:79], v[78:79], v[214:215] op_sel:[0,1] op_sel_hi:[1,1]
	v_pk_mul_f32 v[76:77], v[76:77], v[214:215] op_sel:[0,1] op_sel_hi:[1,1]
	v_pk_mul_f32 v[110:111], v[110:111], v[214:215] op_sel:[0,1] op_sel_hi:[1,1]
	v_pk_mul_f32 v[108:109], v[108:109], v[214:215] op_sel:[0,1] op_sel_hi:[1,1]

.LBB0_850:
	s_and_b32 s2, s11, 7
	v_readlane_b32 s3, v254, 16
	s_lshl_b32 s2, s2, 8
	v_mov_b32_e32 v160, 0
	v_add_u32_e32 v0, s3, v239
	v_add_u32_e32 v0, s2, v0
	v_ashrrev_i32_e32 v1, 31, v0
	v_lshlrev_b64 v[0:1], 11, v[0:1]
	v_readlane_b32 s3, v254, 6
	v_lshl_add_u64 v[192:193], v[204:205], 0, v[0:1]
	s_mov_b64 s[8:9], 0
	v_add_u32_e32 v0, s3, v239
	v_add_u32_e32 v0, s2, v0
	v_ashrrev_i32_e32 v1, 31, v0
	v_lshlrev_b64 v[0:1], 11, v[0:1]
	v_readlane_b32 s3, v254, 7
	v_lshl_add_u64 v[194:195], v[204:205], 0, v[0:1]
	v_mov_b32_e32 v161, v160
	v_add_u32_e32 v0, s3, v239
	v_add_u32_e32 v0, s2, v0
	v_ashrrev_i32_e32 v1, 31, v0
	v_lshlrev_b64 v[0:1], 11, v[0:1]
	v_readlane_b32 s3, v254, 8
	v_lshl_add_u64 v[208:209], v[204:205], 0, v[0:1]
	v_mov_b32_e32 v162, v160
	v_add_u32_e32 v0, s3, v239
	v_add_u32_e32 v0, s2, v0
	v_ashrrev_i32_e32 v1, 31, v0
	v_lshlrev_b64 v[0:1], 11, v[0:1]
	v_readlane_b32 s3, v254, 13
	v_lshl_add_u64 v[210:211], v[204:205], 0, v[0:1]
	v_mov_b32_e32 v163, v160
	v_add_u32_e32 v0, s3, v239
	v_add_u32_e32 v0, s2, v0
	v_ashrrev_i32_e32 v1, 31, v0
	v_lshlrev_b64 v[0:1], 11, v[0:1]
	v_readlane_b32 s3, v254, 14
	v_lshl_add_u64 v[212:213], v[204:205], 0, v[0:1]
	v_mov_b32_e32 v164, v160
	v_add_u32_e32 v0, s3, v239
	v_add_u32_e32 v0, s2, v0
	v_ashrrev_i32_e32 v1, 31, v0
	v_lshlrev_b64 v[0:1], 11, v[0:1]
	v_readlane_b32 s3, v254, 15
	v_lshl_add_u64 v[214:215], v[204:205], 0, v[0:1]
	v_mov_b32_e32 v165, v160
	v_add_u32_e32 v0, s3, v239
	v_add_u32_e32 v0, s2, v0
	v_ashrrev_i32_e32 v1, 31, v0
	v_lshlrev_b64 v[0:1], 11, v[0:1]
	v_readlane_b32 s3, v254, 17
	v_lshl_add_u64 v[216:217], v[204:205], 0, v[0:1]
	v_mov_b32_e32 v166, v160
	v_add_u32_e32 v0, s3, v239
	v_add_u32_e32 v0, s2, v0
	v_ashrrev_i32_e32 v1, 31, v0
	v_lshlrev_b64 v[0:1], 11, v[0:1]
	s_and_b32 s2, s10, 0x1f80
	v_lshl_add_u64 v[218:219], v[204:205], 0, v[0:1]
	v_add_u32_e32 v0, s2, v239
	v_ashrrev_i32_e32 v1, 31, v0
	v_lshlrev_b64 v[0:1], 11, v[0:1]
	v_lshl_add_u64 v[220:221], v[206:207], 0, v[0:1]
	v_add_u32_e32 v0, s2, v242
	v_ashrrev_i32_e32 v1, 31, v0
	v_lshlrev_b64 v[0:1], 11, v[0:1]
	v_lshl_add_u64 v[222:223], v[206:207], 0, v[0:1]
	v_add_u32_e32 v0, s2, v243
	v_ashrrev_i32_e32 v1, 31, v0
	v_lshlrev_b64 v[0:1], 11, v[0:1]
	v_lshl_add_u64 v[224:225], v[206:207], 0, v[0:1]
	v_add_u32_e32 v0, s2, v244
	s_and_b32 s2, s12, 7
	v_ashrrev_i32_e32 v1, 31, v0
	s_or_b32 s2, s2, s33
	v_lshlrev_b64 v[0:1], 11, v[0:1]
	s_lshl_b32 s13, s2, 8
	v_lshl_add_u64 v[226:227], v[206:207], 0, v[0:1]
	v_add_u32_e32 v0, s13, v239
	v_ashrrev_i32_e32 v1, 31, v0
	v_lshlrev_b64 v[0:1], 11, v[0:1]
	v_lshl_add_u64 v[24:25], v[198:199], 0, v[0:1]
	s_mov_b32 s2, 0x10000
	v_add_co_u32_e32 v4, vcc, s2, v24
	s_mov_b32 s2, 0x20000
	s_nop 0
	v_addc_co_u32_e32 v5, vcc, 0, v25, vcc
	v_add_co_u32_e32 v8, vcc, s2, v24
	s_mov_b32 s2, 0x30000
	s_nop 0
	v_addc_co_u32_e32 v9, vcc, 0, v25, vcc
	v_add_co_u32_e32 v12, vcc, s2, v24
	s_mov_b32 s2, 0x40000
	s_nop 0
	v_addc_co_u32_e32 v13, vcc, 0, v25, vcc
	v_add_co_u32_e32 v16, vcc, s2, v24
	s_mov_b32 s2, 0x50000
	s_nop 0
	v_addc_co_u32_e32 v17, vcc, 0, v25, vcc
	s_lshl_b32 s3, s12, 4
	v_add_co_u32_e32 v20, vcc, s2, v24
	s_mov_b32 s2, 0x60000
	s_nop 0
	v_addc_co_u32_e32 v21, vcc, 0, v25, vcc
	s_and_b32 s14, s3, 0x1f80
	v_add_co_u32_e32 v26, vcc, s2, v24
	v_add_u32_e32 v32, s14, v239
	s_nop 0
	v_addc_co_u32_e32 v27, vcc, 0, v25, vcc
	v_ashrrev_i32_e32 v33, 31, v32
	v_add_co_u32_e32 v28, vcc, 0x70000, v24
	v_lshlrev_b64 v[32:33], 11, v[32:33]
	s_nop 0
	v_addc_co_u32_e32 v29, vcc, 0, v25, vcc
	v_lshl_add_u64 v[40:41], v[200:201], 0, v[32:33]
	v_add_co_u32_e32 v36, vcc, 0x10000, v40
	global_load_dwordx4 v[0:3], v[24:25], off sc1
	s_nop 0
	global_load_dwordx4 v[4:7], v[4:5], off sc1
	v_addc_co_u32_e32 v37, vcc, 0, v41, vcc
	v_add_co_u32_e32 v42, vcc, 0x20000, v40
	global_load_dwordx4 v[8:11], v[8:9], off sc1
	s_nop 0
	global_load_dwordx4 v[12:15], v[12:13], off sc1
	v_addc_co_u32_e32 v43, vcc, 0, v41, vcc
	v_add_co_u32_e32 v44, vcc, 0x30000, v40
	global_load_dwordx4 v[16:19], v[16:17], off sc1
	s_nop 0
	global_load_dwordx4 v[20:23], v[20:21], off sc1
	v_addc_co_u32_e32 v45, vcc, 0, v41, vcc
	global_load_dwordx4 v[24:27], v[26:27], off sc1
	s_nop 0
	global_load_dwordx4 v[28:31], v[28:29], off sc1
	s_nop 0
	global_load_dwordx4 v[32:35], v[40:41], off sc1
	s_nop 0
	global_load_dwordx4 v[36:39], v[36:37], off sc1
	s_nop 0
	global_load_dwordx4 v[40:43], v[42:43], off sc1
	s_nop 0
	global_load_dwordx4 v[44:47], v[44:45], off sc1
	v_mov_b32_e32 v167, v160
	v_mov_b32_e32 v168, v160
	v_mov_b32_e32 v169, v160
	v_mov_b32_e32 v170, v160
	v_mov_b32_e32 v171, v160
	v_mov_b32_e32 v172, v160
	v_mov_b32_e32 v173, v160
	v_mov_b32_e32 v174, v160
	v_mov_b32_e32 v175, v160
	v_mov_b32_e32 v144, v160
	v_mov_b32_e32 v145, v160
	v_mov_b32_e32 v146, v160
	v_mov_b32_e32 v147, v160
	v_mov_b32_e32 v148, v160
	v_mov_b32_e32 v149, v160
	v_mov_b32_e32 v150, v160
	v_mov_b32_e32 v151, v160
	v_mov_b32_e32 v152, v160
	v_mov_b32_e32 v153, v160
	v_mov_b32_e32 v154, v160
	v_mov_b32_e32 v155, v160
	v_mov_b32_e32 v156, v160
	v_mov_b32_e32 v157, v160
	v_mov_b32_e32 v158, v160
	v_mov_b32_e32 v159, v160
	v_mov_b32_e32 v116, v160
	v_mov_b32_e32 v117, v160
	v_mov_b32_e32 v118, v160
	v_mov_b32_e32 v119, v160
	v_mov_b32_e32 v128, v160
	v_mov_b32_e32 v129, v160
	v_mov_b32_e32 v130, v160
	v_mov_b32_e32 v131, v160
	v_mov_b32_e32 v136, v160
	v_mov_b32_e32 v137, v160
	v_mov_b32_e32 v138, v160
	v_mov_b32_e32 v139, v160
	v_mov_b32_e32 v140, v160
	v_mov_b32_e32 v141, v160
	v_mov_b32_e32 v142, v160
	v_mov_b32_e32 v143, v160
	v_mov_b32_e32 v100, v160
	v_mov_b32_e32 v101, v160
	v_mov_b32_e32 v102, v160
	v_mov_b32_e32 v103, v160
	v_mov_b32_e32 v112, v160
	v_mov_b32_e32 v113, v160
	v_mov_b32_e32 v114, v160
	v_mov_b32_e32 v115, v160
	v_mov_b32_e32 v124, v160
	v_mov_b32_e32 v125, v160
	v_mov_b32_e32 v126, v160
	v_mov_b32_e32 v127, v160
	v_mov_b32_e32 v132, v160
	v_mov_b32_e32 v133, v160
	v_mov_b32_e32 v134, v160
	v_mov_b32_e32 v135, v160
	v_mov_b32_e32 v76, v160
	v_mov_b32_e32 v77, v160
	v_mov_b32_e32 v78, v160
	v_mov_b32_e32 v79, v160
	v_mov_b32_e32 v96, v160
	v_mov_b32_e32 v97, v160
	v_mov_b32_e32 v98, v160
	v_mov_b32_e32 v99, v160
	v_mov_b32_e32 v108, v160
	v_mov_b32_e32 v109, v160
	v_mov_b32_e32 v110, v160
	v_mov_b32_e32 v111, v160
	v_mov_b32_e32 v120, v160
	v_mov_b32_e32 v121, v160
	v_mov_b32_e32 v122, v160
	v_mov_b32_e32 v123, v160
	v_mov_b32_e32 v60, v160
	v_mov_b32_e32 v61, v160
	v_mov_b32_e32 v62, v160
	v_mov_b32_e32 v63, v160
	v_mov_b32_e32 v68, v160
	v_mov_b32_e32 v69, v160
	v_mov_b32_e32 v70, v160
	v_mov_b32_e32 v71, v160
	v_mov_b32_e32 v92, v160
	v_mov_b32_e32 v93, v160
	v_mov_b32_e32 v94, v160
	v_mov_b32_e32 v95, v160
	v_mov_b32_e32 v104, v160
	v_mov_b32_e32 v105, v160
	v_mov_b32_e32 v106, v160
	v_mov_b32_e32 v107, v160
	v_mov_b32_e32 v52, v160
	v_mov_b32_e32 v53, v160
	v_mov_b32_e32 v54, v160
	v_mov_b32_e32 v55, v160
	v_mov_b32_e32 v56, v160
	v_mov_b32_e32 v57, v160
	v_mov_b32_e32 v58, v160
	v_mov_b32_e32 v59, v160
	v_mov_b32_e32 v64, v160
	v_mov_b32_e32 v65, v160
	v_mov_b32_e32 v66, v160
	v_mov_b32_e32 v67, v160
	v_mov_b32_e32 v84, v160
	v_mov_b32_e32 v85, v160
	v_mov_b32_e32 v86, v160
	v_mov_b32_e32 v87, v160
	v_mov_b32_e32 v88, v160
	v_mov_b32_e32 v89, v160
	v_mov_b32_e32 v90, v160
	v_mov_b32_e32 v91, v160
	v_mov_b32_e32 v80, v160
	v_mov_b32_e32 v81, v160
	v_mov_b32_e32 v82, v160
	v_mov_b32_e32 v83, v160
	v_mov_b32_e32 v72, v160
	v_mov_b32_e32 v73, v160
	v_mov_b32_e32 v74, v160
	v_mov_b32_e32 v75, v160
	v_mov_b32_e32 v48, v160
	v_mov_b32_e32 v49, v160
	v_mov_b32_e32 v50, v160
	v_mov_b32_e32 v51, v160
	v_readfirstlane_b32 s76, v192
	v_readfirstlane_b32 s77, v193
	s_sub_u32 s76, s76, 0x100000
	s_subb_u32 s77, s77, 0
	v_readfirstlane_b32 s78, v220
	v_readfirstlane_b32 s79, v221
	s_sub_u32 s78, s78, 0x100000
	s_subb_u32 s79, s79, 0
	v_subrev_u32_e32 v192, s76, v192
	v_subrev_u32_e32 v194, s76, v194
	v_subrev_u32_e32 v208, s76, v208
	v_subrev_u32_e32 v210, s76, v210
	v_subrev_u32_e32 v212, s76, v212
	v_subrev_u32_e32 v214, s76, v214
	v_subrev_u32_e32 v216, s76, v216
	v_subrev_u32_e32 v218, s76, v218
	v_subrev_u32_e32 v220, s78, v220
	v_subrev_u32_e32 v222, s78, v222
	v_subrev_u32_e32 v224, s78, v224
	v_subrev_u32_e32 v226, s78, v226
.LBB0_851:
	s_waitcnt vmcnt(63) expcnt(7) lgkmcnt(15)
	s_barrier
	s_waitcnt vmcnt(11)
	ds_write_b128 v245, v[0:3]
	s_waitcnt vmcnt(10)
	ds_write_b128 v245, v[4:7] offset:5120
	s_waitcnt vmcnt(9)
	ds_write_b128 v245, v[8:11] offset:10240
	s_waitcnt vmcnt(8)
	ds_write_b128 v245, v[12:15] offset:15360
	s_waitcnt vmcnt(7)
	ds_write_b128 v245, v[16:19] offset:20480
	s_waitcnt vmcnt(6)
	ds_write_b128 v245, v[20:23] offset:25600
	s_waitcnt vmcnt(5)
	ds_write_b128 v245, v[24:27] offset:30720
	s_waitcnt vmcnt(4)
	ds_write_b128 v245, v[28:31] offset:35840
	s_waitcnt vmcnt(3)
	ds_write_b128 v245, v[32:35] offset:40960
	s_waitcnt vmcnt(2)
	ds_write_b128 v245, v[36:39] offset:46080
	s_waitcnt vmcnt(1)
	ds_write_b128 v245, v[40:43] offset:51200
	s_waitcnt vmcnt(0)
	ds_write_b128 v245, v[44:47] offset:56320
	s_add_u32 s80, s76, s8
	s_addc_u32 s81, s77, s9
	s_add_u32 s82, s78, s8
	s_addc_u32 s83, s79, s9
	s_waitcnt lgkmcnt(0)
	s_barrier
	global_load_dwordx4 v[0:3], v192, s[80:81] sc1
	global_load_dwordx4 v[4:7], v194, s[80:81] sc1
	global_load_dwordx4 v[8:11], v208, s[80:81] sc1
	global_load_dwordx4 v[12:15], v210, s[80:81] sc1
	global_load_dwordx4 v[16:19], v212, s[80:81] sc1
	global_load_dwordx4 v[20:23], v214, s[80:81] sc1
	global_load_dwordx4 v[24:27], v216, s[80:81] sc1
	global_load_dwordx4 v[28:31], v218, s[80:81] sc1
	global_load_dwordx4 v[32:35], v220, s[82:83] sc1
	global_load_dwordx4 v[36:39], v222, s[82:83] sc1
	global_load_dwordx4 v[40:43], v224, s[82:83] sc1
	global_load_dwordx4 v[44:47], v226, s[82:83] sc1
	ds_read_b128 v[176:179], v246 offset:40960
	ds_read_b128 v[184:187], v246 offset:43520
	ds_read_b128 v[188:191], v246 offset:46080
	ds_read_b128 v[230:233], v246 offset:48640
	ds_read_b128 v[180:183], v241
	ds_read_b128 v[248:251], v241 offset:2560
	s_add_u32 s8, s8, 0x80
	s_addc_u32 s9, s9, 0
	s_waitcnt lgkmcnt(1)
	v_mfma_f32_16x16x32_bf16 v[48:51], v[176:179], v[180:183], v[48:51]
	v_mfma_f32_16x16x32_bf16 v[72:75], v[184:187], v[180:183], v[72:75]
	v_mfma_f32_16x16x32_bf16 v[80:83], v[188:191], v[180:183], v[80:83]
	v_mfma_f32_16x16x32_bf16 v[88:91], v[230:233], v[180:183], v[88:91]
	ds_read_b128 v[180:183], v241 offset:5120
	s_waitcnt lgkmcnt(1)
	v_mfma_f32_16x16x32_bf16 v[84:87], v[176:179], v[248:251], v[84:87]
	v_mfma_f32_16x16x32_bf16 v[64:67], v[184:187], v[248:251], v[64:67]
	v_mfma_f32_16x16x32_bf16 v[56:59], v[188:191], v[248:251], v[56:59]
	v_mfma_f32_16x16x32_bf16 v[52:55], v[230:233], v[248:251], v[52:55]
	ds_read_b128 v[248:251], v241 offset:7680
	s_waitcnt lgkmcnt(1)
	v_mfma_f32_16x16x32_bf16 v[104:107], v[176:179], v[180:183], v[104:107]
	v_mfma_f32_16x16x32_bf16 v[92:95], v[184:187], v[180:183], v[92:95]
	v_mfma_f32_16x16x32_bf16 v[68:71], v[188:191], v[180:183], v[68:71]
	v_mfma_f32_16x16x32_bf16 v[60:63], v[230:233], v[180:183], v[60:63]
	ds_read_b128 v[180:183], v241 offset:10240
	s_waitcnt lgkmcnt(1)
	v_mfma_f32_16x16x32_bf16 v[120:123], v[176:179], v[248:251], v[120:123]
	v_mfma_f32_16x16x32_bf16 v[108:111], v[184:187], v[248:251], v[108:111]
	v_mfma_f32_16x16x32_bf16 v[96:99], v[188:191], v[248:251], v[96:99]
	v_mfma_f32_16x16x32_bf16 v[76:79], v[230:233], v[248:251], v[76:79]
	ds_read_b128 v[248:251], v241 offset:12800
	s_waitcnt lgkmcnt(1)
	v_mfma_f32_16x16x32_bf16 v[132:135], v[176:179], v[180:183], v[132:135]
	v_mfma_f32_16x16x32_bf16 v[124:127], v[184:187], v[180:183], v[124:127]
	v_mfma_f32_16x16x32_bf16 v[112:115], v[188:191], v[180:183], v[112:115]
	v_mfma_f32_16x16x32_bf16 v[100:103], v[230:233], v[180:183], v[100:103]
	ds_read_b128 v[180:183], v241 offset:15360
	s_waitcnt lgkmcnt(1)
	v_mfma_f32_16x16x32_bf16 v[140:143], v[176:179], v[248:251], v[140:143]
	v_mfma_f32_16x16x32_bf16 v[136:139], v[184:187], v[248:251], v[136:139]
	v_mfma_f32_16x16x32_bf16 v[128:131], v[188:191], v[248:251], v[128:131]
	v_mfma_f32_16x16x32_bf16 v[116:119], v[230:233], v[248:251], v[116:119]
	ds_read_b128 v[248:251], v247
	s_waitcnt lgkmcnt(1)
	v_mfma_f32_16x16x32_bf16 v[156:159], v[176:179], v[180:183], v[156:159]
	v_mfma_f32_16x16x32_bf16 v[152:155], v[184:187], v[180:183], v[152:155]
	v_mfma_f32_16x16x32_bf16 v[148:151], v[188:191], v[180:183], v[148:151]
	v_mfma_f32_16x16x32_bf16 v[144:147], v[230:233], v[180:183], v[144:147]
	ds_read_b128 v[180:183], v241 offset:64
	s_waitcnt lgkmcnt(1)
	v_mfma_f32_16x16x32_bf16 v[172:175], v[176:179], v[248:251], v[172:175]
	ds_read_b128 v[176:179], v246 offset:41024
	v_mfma_f32_16x16x32_bf16 v[168:171], v[184:187], v[248:251], v[168:171]
	ds_read_b128 v[184:187], v246 offset:43584
	v_mfma_f32_16x16x32_bf16 v[164:167], v[188:191], v[248:251], v[164:167]
	ds_read_b128 v[188:191], v246 offset:46144
	v_mfma_f32_16x16x32_bf16 v[160:163], v[230:233], v[248:251], v[160:163]
	ds_read_b128 v[230:233], v246 offset:48704
	ds_read_b128 v[248:251], v241 offset:2624
	s_waitcnt lgkmcnt(1)
	v_mfma_f32_16x16x32_bf16 v[48:51], v[176:179], v[180:183], v[48:51]
	v_mfma_f32_16x16x32_bf16 v[72:75], v[184:187], v[180:183], v[72:75]
	v_mfma_f32_16x16x32_bf16 v[80:83], v[188:191], v[180:183], v[80:83]
	v_mfma_f32_16x16x32_bf16 v[88:91], v[230:233], v[180:183], v[88:91]
	ds_read_b128 v[180:183], v241 offset:5184
	s_waitcnt lgkmcnt(1)
	v_mfma_f32_16x16x32_bf16 v[84:87], v[176:179], v[248:251], v[84:87]
	v_mfma_f32_16x16x32_bf16 v[64:67], v[184:187], v[248:251], v[64:67]
	v_mfma_f32_16x16x32_bf16 v[56:59], v[188:191], v[248:251], v[56:59]
	v_mfma_f32_16x16x32_bf16 v[52:55], v[230:233], v[248:251], v[52:55]
	ds_read_b128 v[248:251], v241 offset:7744
	s_waitcnt lgkmcnt(1)
	v_mfma_f32_16x16x32_bf16 v[104:107], v[176:179], v[180:183], v[104:107]
	v_mfma_f32_16x16x32_bf16 v[92:95], v[184:187], v[180:183], v[92:95]
	v_mfma_f32_16x16x32_bf16 v[68:71], v[188:191], v[180:183], v[68:71]
	v_mfma_f32_16x16x32_bf16 v[60:63], v[230:233], v[180:183], v[60:63]
	ds_read_b128 v[180:183], v241 offset:10304
	s_waitcnt lgkmcnt(1)
	v_mfma_f32_16x16x32_bf16 v[120:123], v[176:179], v[248:251], v[120:123]
	v_mfma_f32_16x16x32_bf16 v[108:111], v[184:187], v[248:251], v[108:111]
	v_mfma_f32_16x16x32_bf16 v[96:99], v[188:191], v[248:251], v[96:99]
	v_mfma_f32_16x16x32_bf16 v[76:79], v[230:233], v[248:251], v[76:79]
	ds_read_b128 v[248:251], v241 offset:12864
	s_waitcnt lgkmcnt(1)
	v_mfma_f32_16x16x32_bf16 v[132:135], v[176:179], v[180:183], v[132:135]
	v_mfma_f32_16x16x32_bf16 v[124:127], v[184:187], v[180:183], v[124:127]
	v_mfma_f32_16x16x32_bf16 v[112:115], v[188:191], v[180:183], v[112:115]
	v_mfma_f32_16x16x32_bf16 v[100:103], v[230:233], v[180:183], v[100:103]
	ds_read_b128 v[180:183], v241 offset:15424
	s_waitcnt lgkmcnt(1)
	v_mfma_f32_16x16x32_bf16 v[140:143], v[176:179], v[248:251], v[140:143]
	v_mfma_f32_16x16x32_bf16 v[136:139], v[184:187], v[248:251], v[136:139]
	v_mfma_f32_16x16x32_bf16 v[128:131], v[188:191], v[248:251], v[128:131]
	v_mfma_f32_16x16x32_bf16 v[116:119], v[230:233], v[248:251], v[116:119]
	ds_read_b128 v[248:251], v247 offset:64
	s_waitcnt lgkmcnt(1)
	v_mfma_f32_16x16x32_bf16 v[156:159], v[176:179], v[180:183], v[156:159]
	v_mfma_f32_16x16x32_bf16 v[152:155], v[184:187], v[180:183], v[152:155]
	v_mfma_f32_16x16x32_bf16 v[148:151], v[188:191], v[180:183], v[148:151]
	v_mfma_f32_16x16x32_bf16 v[144:147], v[230:233], v[180:183], v[144:147]
	s_waitcnt lgkmcnt(0)
	v_mfma_f32_16x16x32_bf16 v[172:175], v[176:179], v[248:251], v[172:175]
	v_mfma_f32_16x16x32_bf16 v[168:171], v[184:187], v[248:251], v[168:171]
	v_mfma_f32_16x16x32_bf16 v[164:167], v[188:191], v[248:251], v[164:167]
	v_mfma_f32_16x16x32_bf16 v[160:163], v[230:233], v[248:251], v[160:163]
	s_cmpk_eq_i32 s8, 0x780
	s_cbranch_scc0 .LBB0_851
	s_barrier
	s_waitcnt vmcnt(11)
	ds_write_b128 v245, v[0:3]
	s_waitcnt vmcnt(10)
	ds_write_b128 v245, v[4:7] offset:5120
	s_waitcnt vmcnt(9)
	ds_write_b128 v245, v[8:11] offset:10240
	s_waitcnt vmcnt(8)
	ds_write_b128 v245, v[12:15] offset:15360
	s_waitcnt vmcnt(7)
	ds_write_b128 v245, v[16:19] offset:20480
	s_waitcnt vmcnt(6)
	ds_write_b128 v245, v[20:23] offset:25600
	s_waitcnt vmcnt(5)
	ds_write_b128 v245, v[24:27] offset:30720
	s_waitcnt vmcnt(4)
	ds_write_b128 v245, v[28:31] offset:35840
	s_waitcnt vmcnt(3)
	ds_write_b128 v245, v[32:35] offset:40960
	s_waitcnt vmcnt(2)
	ds_write_b128 v245, v[36:39] offset:46080
	s_waitcnt vmcnt(1)
	ds_write_b128 v245, v[40:43] offset:51200
	s_waitcnt vmcnt(0)
	ds_write_b128 v245, v[44:47] offset:56320
	s_waitcnt lgkmcnt(0)
	s_barrier
	ds_read_b128 v[208:211], v246 offset:40960
	ds_read_b128 v[212:215], v246 offset:43520
	ds_read_b128 v[216:219], v246 offset:46080
	ds_read_b128 v[220:223], v246 offset:48640
	ds_read_b128 v[0:3], v241
	ds_read_b128 v[4:7], v241 offset:2560
	ds_read_b128 v[8:11], v241 offset:5120
	ds_read_b128 v[12:15], v241 offset:12800
	v_or_b32_e32 v196, s14, v238
	s_waitcnt lgkmcnt(3)
	v_mfma_f32_16x16x32_bf16 v[180:183], v[208:211], v[0:3], v[48:51]
	s_add_i32 s12, s12, s53
	s_add_i32 s11, s11, s53
	v_mfma_f32_16x16x32_bf16 v[184:187], v[212:215], v[0:3], v[72:75]
	v_mfma_f32_16x16x32_bf16 v[188:191], v[216:219], v[0:3], v[80:83]
	v_mfma_f32_16x16x32_bf16 v[192:195], v[220:223], v[0:3], v[88:91]
	ds_read_b128 v[0:3], v241 offset:7680
	s_waitcnt lgkmcnt(3)
	v_mfma_f32_16x16x32_bf16 v[80:83], v[208:211], v[4:7], v[84:87]
	v_mfma_f32_16x16x32_bf16 v[84:87], v[212:215], v[4:7], v[64:67]
	v_mfma_f32_16x16x32_bf16 v[88:91], v[216:219], v[4:7], v[56:59]
	v_mfma_f32_16x16x32_bf16 v[176:179], v[220:223], v[4:7], v[52:55]
	ds_read_b128 v[4:7], v241 offset:10240
	s_waitcnt lgkmcnt(3)
	v_mfma_f32_16x16x32_bf16 v[72:75], v[212:215], v[8:11], v[92:95]
	s_waitcnt lgkmcnt(1)
	v_mfma_f32_16x16x32_bf16 v[56:59], v[220:223], v[0:3], v[76:79]
	s_nop 0
	ds_read_b128 v[92:95], v247
	s_nop 0
	ds_read_b128 v[76:79], v241 offset:15360
	v_mfma_f32_16x16x32_bf16 v[64:67], v[208:211], v[8:11], v[104:107]
	v_mfma_f32_16x16x32_bf16 v[68:71], v[216:219], v[8:11], v[68:71]
	v_mfma_f32_16x16x32_bf16 v[60:63], v[220:223], v[8:11], v[60:63]
	v_mfma_f32_16x16x32_bf16 v[44:47], v[208:211], v[0:3], v[120:123]
	s_waitcnt lgkmcnt(2)
	v_mfma_f32_16x16x32_bf16 v[28:31], v[208:211], v[4:7], v[132:135]
	v_mfma_f32_16x16x32_bf16 v[32:35], v[212:215], v[4:7], v[124:127]
	v_mfma_f32_16x16x32_bf16 v[36:39], v[216:219], v[4:7], v[112:115]
	v_mfma_f32_16x16x32_bf16 v[40:43], v[220:223], v[4:7], v[100:103]
	v_mfma_f32_16x16x32_bf16 v[4:7], v[212:215], v[12:15], v[136:139]
	v_mfma_f32_16x16x32_bf16 v[8:11], v[216:219], v[12:15], v[128:131]
	s_waitcnt lgkmcnt(0)
	v_mfma_f32_16x16x32_bf16 v[16:19], v[208:211], v[76:79], v[156:159]
	v_mfma_f32_16x16x32_bf16 v[20:23], v[212:215], v[76:79], v[152:155]
	v_mfma_f32_16x16x32_bf16 v[24:27], v[216:219], v[76:79], v[148:151]
	v_mfma_f32_16x16x32_bf16 v[120:123], v[220:223], v[76:79], v[144:147]
	v_mfma_f32_16x16x32_bf16 v[124:127], v[208:211], v[92:95], v[172:175]
	v_mfma_f32_16x16x32_bf16 v[128:131], v[212:215], v[92:95], v[168:171]
	v_mfma_f32_16x16x32_bf16 v[132:135], v[216:219], v[92:95], v[164:167]
	v_mfma_f32_16x16x32_bf16 v[136:139], v[220:223], v[92:95], v[160:163]
	ds_read_b128 v[148:151], v246 offset:41024
	ds_read_b128 v[152:155], v246 offset:43584
	ds_read_b128 v[156:159], v246 offset:46144
	ds_read_b128 v[160:163], v246 offset:48704
	ds_read_b128 v[76:79], v241 offset:64
	ds_read_b128 v[92:95], v241 offset:2624
	ds_read_b128 v[164:167], v241 offset:5184
	ds_read_b128 v[168:171], v241 offset:7744
	ds_read_b128 v[172:175], v241 offset:10304
	v_mfma_f32_16x16x32_bf16 v[48:51], v[212:215], v[0:3], v[108:111]
	v_mfma_f32_16x16x32_bf16 v[52:55], v[216:219], v[0:3], v[96:99]
	v_mfma_f32_16x16x32_bf16 v[0:3], v[208:211], v[12:15], v[140:143]
	v_mfma_f32_16x16x32_bf16 v[12:15], v[220:223], v[12:15], v[116:119]
	s_waitcnt lgkmcnt(4)
	v_mfma_f32_16x16x32_bf16 v[144:147], v[148:151], v[76:79], v[180:183]
	v_mfma_f32_16x16x32_bf16 v[116:119], v[152:155], v[76:79], v[184:187]
	v_mfma_f32_16x16x32_bf16 v[140:143], v[156:159], v[76:79], v[188:191]
	v_mfma_f32_16x16x32_bf16 v[112:115], v[160:163], v[76:79], v[192:195]
	s_waitcnt lgkmcnt(3)
	v_mfma_f32_16x16x32_bf16 v[108:111], v[148:151], v[92:95], v[80:83]
	v_mfma_f32_16x16x32_bf16 v[100:103], v[152:155], v[92:95], v[84:87]
	v_mfma_f32_16x16x32_bf16 v[104:107], v[156:159], v[92:95], v[88:91]
	v_mfma_f32_16x16x32_bf16 v[96:99], v[160:163], v[92:95], v[176:179]
	s_waitcnt lgkmcnt(2)
	v_mfma_f32_16x16x32_bf16 v[92:95], v[148:151], v[164:167], v[64:67]
	v_mfma_f32_16x16x32_bf16 v[84:87], v[152:155], v[164:167], v[72:75]
	v_mfma_f32_16x16x32_bf16 v[88:91], v[156:159], v[164:167], v[68:71]
	v_mfma_f32_16x16x32_bf16 v[80:83], v[160:163], v[164:167], v[60:63]
	ds_read_b128 v[164:167], v241 offset:12864
	s_waitcnt lgkmcnt(2)
	v_mfma_f32_16x16x32_bf16 v[76:79], v[148:151], v[168:171], v[44:47]
	v_mfma_f32_16x16x32_bf16 v[68:71], v[152:155], v[168:171], v[48:51]
	v_mfma_f32_16x16x32_bf16 v[72:75], v[156:159], v[168:171], v[52:55]
	v_mfma_f32_16x16x32_bf16 v[64:67], v[160:163], v[168:171], v[56:59]
	ds_read_b128 v[168:171], v241 offset:15424
	s_waitcnt lgkmcnt(2)
	v_mfma_f32_16x16x32_bf16 v[60:63], v[148:151], v[172:175], v[28:31]
	s_waitcnt lgkmcnt(0)
	v_mfma_f32_16x16x32_bf16 v[28:31], v[148:151], v[168:171], v[16:19]
	v_mfma_f32_16x16x32_bf16 v[16:19], v[160:163], v[168:171], v[120:123]
	s_nop 2
	v_mul_f32_e32 v123, 0xbfb8aa3b, v144
	v_mfma_f32_16x16x32_bf16 v[52:55], v[152:155], v[172:175], v[32:35]
	v_exp_f32_e32 v123, v123
	v_add_u32_e32 v122, s13, v240
	v_lshl_add_u64 v[120:121], v[202:203], 0, v[196:197]
	v_mfma_f32_16x16x32_bf16 v[56:59], v[156:159], v[172:175], v[36:39]
	v_add_f32_e32 v123, 1.0, v123
	v_mfma_f32_16x16x32_bf16 v[48:51], v[160:163], v[172:175], v[40:43]
	ds_read_b128 v[172:175], v247 offset:64
	v_mfma_f32_16x16x32_bf16 v[32:35], v[160:163], v[164:167], v[12:15]
	s_waitcnt lgkmcnt(0)
	v_mfma_f32_16x16x32_bf16 v[12:15], v[148:151], v[172:175], v[124:127]
	s_nop 2
	v_rcp_f32_e32 v126, v123
	v_mul_f32_e32 v123, 0xbfb8aa3b, v145
	v_exp_f32_e32 v123, v123
	v_mfma_f32_16x16x32_bf16 v[36:39], v[152:155], v[164:167], v[4:7]
	v_mad_i64_i32 v[124:125], s[2:3], v122, s46, v[120:121]
	v_add_f32_e32 v123, 1.0, v123
	v_rcp_f32_e32 v127, v123
	v_mul_f32_e32 v123, 0xbfb8aa3b, v146
	v_exp_f32_e32 v123, v123
	v_mfma_f32_16x16x32_bf16 v[4:7], v[152:155], v[172:175], v[128:131]
	v_mul_f32_e64 v126, v144, v126
	v_mul_f32_e64 v127, v145, v127
	v_add_f32_e32 v123, 1.0, v123
	v_rcp_f32_e32 v128, v123
	v_mul_f32_e32 v123, 0xbfb8aa3b, v147
	v_exp_f32_e32 v123, v123
	v_pk_mul_f32 v[126:127], v[140:141], v[126:127]
	v_mfma_f32_16x16x32_bf16 v[44:47], v[148:151], v[164:167], v[0:3]
	v_cvt_pk_bf16_f32 v126, v126, v127
	v_add_f32_e32 v123, 1.0, v123
	v_rcp_f32_e32 v129, v123
	v_mul_f32_e32 v123, 0xbfb8aa3b, v116
	v_exp_f32_e32 v123, v123
	v_mfma_f32_16x16x32_bf16 v[40:43], v[156:159], v[164:167], v[8:11]
	v_mul_f32_e64 v128, v146, v128
	v_mul_f32_e64 v129, v147, v129
	v_add_f32_e32 v123, 1.0, v123
	v_pk_mul_f32 v[128:129], v[142:143], v[128:129]
	v_mfma_f32_16x16x32_bf16 v[24:27], v[156:159], v[168:171], v[24:27]
	v_cvt_pk_bf16_f32 v127, v128, v129
	global_store_dwordx2 v[124:125], v[126:127], off
	v_rcp_f32_e32 v126, v123
	v_mul_f32_e32 v123, 0xbfb8aa3b, v117
	v_exp_f32_e32 v123, v123
	v_mfma_f32_16x16x32_bf16 v[20:23], v[152:155], v[168:171], v[20:23]
	v_add_f32_e32 v123, 1.0, v123
	v_rcp_f32_e32 v127, v123
	v_mfma_f32_16x16x32_bf16 v[8:11], v[156:159], v[172:175], v[132:135]
	v_mul_f32_e64 v116, v116, v126
	v_mul_f32_e64 v117, v117, v127
	v_pk_mul_f32 v[112:113], v[112:113], v[116:117]
	v_mfma_f32_16x16x32_bf16 v[0:3], v[160:163], v[172:175], v[136:139]
	v_cvt_pk_bf16_f32 v112, v112, v113
	v_mul_f32_e32 v113, 0xbfb8aa3b, v118
	v_exp_f32_e32 v113, v113
	s_nop 0
	v_add_f32_e32 v113, 1.0, v113
	v_rcp_f32_e32 v116, v113
	v_mul_f32_e32 v113, 0xbfb8aa3b, v119
	v_exp_f32_e32 v113, v113
	s_nop 0
	v_add_f32_e32 v113, 1.0, v113
	v_rcp_f32_e32 v117, v113
	s_nop 0
	v_pk_mul_f32 v[116:117], v[118:119], v[116:117]
	s_nop 0
	v_pk_mul_f32 v[114:115], v[114:115], v[116:117]
	s_nop 0
	v_cvt_pk_bf16_f32 v113, v114, v115
	v_mul_f32_e32 v114, 0xbfb8aa3b, v108
	v_mul_f32_e32 v115, 0xbfb8aa3b, v109
	v_exp_f32_e32 v114, v114
	v_exp_f32_e32 v115, v115
	global_store_dwordx2 v[124:125], v[112:113], off offset:32
	v_or_b32_e32 v112, 16, v122
	v_add_f32_e32 v114, 1.0, v114
	v_add_f32_e32 v115, 1.0, v115
	v_rcp_f32_e32 v114, v114
	v_rcp_f32_e32 v115, v115
	v_mad_i64_i32 v[112:113], s[2:3], v112, s46, v[120:121]
	v_pk_mul_f32 v[108:109], v[108:109], v[114:115]
	s_nop 0
	v_pk_mul_f32 v[104:105], v[104:105], v[108:109]
	s_nop 0
	v_cvt_pk_bf16_f32 v104, v104, v105
	v_mul_f32_e32 v105, 0xbfb8aa3b, v110
	v_exp_f32_e32 v105, v105
	s_nop 0
	v_add_f32_e32 v105, 1.0, v105
	v_rcp_f32_e32 v108, v105
	v_mul_f32_e32 v105, 0xbfb8aa3b, v111
	v_exp_f32_e32 v105, v105
	s_nop 0
	v_add_f32_e32 v105, 1.0, v105
	v_rcp_f32_e32 v109, v105
	s_nop 0
	v_pk_mul_f32 v[108:109], v[110:111], v[108:109]
	s_nop 0
	v_pk_mul_f32 v[106:107], v[106:107], v[108:109]
	s_nop 0
	v_cvt_pk_bf16_f32 v105, v106, v107
	global_store_dwordx2 v[112:113], v[104:105], off
	v_mul_f32_e32 v104, 0xbfb8aa3b, v100
	v_mul_f32_e32 v105, 0xbfb8aa3b, v101
	v_exp_f32_e32 v104, v104
	v_exp_f32_e32 v105, v105
	v_add_f32_e32 v104, 1.0, v104
	v_add_f32_e32 v105, 1.0, v105
	v_rcp_f32_e32 v104, v104
	v_rcp_f32_e32 v105, v105
	s_nop 0
	v_pk_mul_f32 v[100:101], v[100:101], v[104:105]
	s_nop 0
	v_pk_mul_f32 v[96:97], v[96:97], v[100:101]
	s_nop 0
	v_cvt_pk_bf16_f32 v96, v96, v97
	v_mul_f32_e32 v97, 0xbfb8aa3b, v102
	v_exp_f32_e32 v97, v97
	s_nop 0
	v_add_f32_e32 v97, 1.0, v97
	v_rcp_f32_e32 v100, v97
	v_mul_f32_e32 v97, 0xbfb8aa3b, v103
	v_exp_f32_e32 v97, v97
	s_nop 0
	v_add_f32_e32 v97, 1.0, v97
	v_rcp_f32_e32 v101, v97
	s_nop 0
	v_pk_mul_f32 v[100:101], v[102:103], v[100:101]
	s_nop 0
	v_pk_mul_f32 v[98:99], v[98:99], v[100:101]
	s_nop 0
	v_cvt_pk_bf16_f32 v97, v98, v99
	v_mul_f32_e32 v98, 0xbfb8aa3b, v92
	v_mul_f32_e32 v99, 0xbfb8aa3b, v93
	v_exp_f32_e32 v98, v98
	v_exp_f32_e32 v99, v99
	global_store_dwordx2 v[112:113], v[96:97], off offset:32
	v_or_b32_e32 v96, 32, v122
	v_add_f32_e32 v98, 1.0, v98
	v_add_f32_e32 v99, 1.0, v99
	v_rcp_f32_e32 v98, v98
	v_rcp_f32_e32 v99, v99
	v_mad_i64_i32 v[96:97], s[2:3], v96, s46, v[120:121]
	v_pk_mul_f32 v[92:93], v[92:93], v[98:99]
	s_nop 0
	v_pk_mul_f32 v[88:89], v[88:89], v[92:93]
	s_nop 0
	v_cvt_pk_bf16_f32 v88, v88, v89
	v_mul_f32_e32 v89, 0xbfb8aa3b, v94
	v_exp_f32_e32 v89, v89
	s_nop 0
	v_add_f32_e32 v89, 1.0, v89
	v_rcp_f32_e32 v92, v89
	v_mul_f32_e32 v89, 0xbfb8aa3b, v95
	v_exp_f32_e32 v89, v89
	s_nop 0
	v_add_f32_e32 v89, 1.0, v89
	v_rcp_f32_e32 v93, v89
	s_nop 0
	v_pk_mul_f32 v[92:93], v[94:95], v[92:93]
	s_nop 0
	v_pk_mul_f32 v[90:91], v[90:91], v[92:93]
	s_nop 0
	v_cvt_pk_bf16_f32 v89, v90, v91
	global_store_dwordx2 v[96:97], v[88:89], off
	v_mul_f32_e32 v88, 0xbfb8aa3b, v84
	v_mul_f32_e32 v89, 0xbfb8aa3b, v85
	v_exp_f32_e32 v88, v88
	v_exp_f32_e32 v89, v89
	v_add_f32_e32 v88, 1.0, v88
	v_add_f32_e32 v89, 1.0, v89
	v_rcp_f32_e32 v88, v88
	v_rcp_f32_e32 v89, v89
	s_nop 0
	v_pk_mul_f32 v[84:85], v[84:85], v[88:89]
	s_nop 0
	v_pk_mul_f32 v[80:81], v[80:81], v[84:85]
	s_nop 0
	v_cvt_pk_bf16_f32 v80, v80, v81
	v_mul_f32_e32 v81, 0xbfb8aa3b, v86
	v_exp_f32_e32 v81, v81
	s_nop 0
	v_add_f32_e32 v81, 1.0, v81
	v_rcp_f32_e32 v84, v81
	v_mul_f32_e32 v81, 0xbfb8aa3b, v87
	v_exp_f32_e32 v81, v81
	s_nop 0
	v_add_f32_e32 v81, 1.0, v81
	v_rcp_f32_e32 v85, v81
	s_nop 0
	v_pk_mul_f32 v[84:85], v[86:87], v[84:85]
	s_nop 0
	v_pk_mul_f32 v[82:83], v[82:83], v[84:85]
	s_nop 0
	v_cvt_pk_bf16_f32 v81, v82, v83
	v_mul_f32_e32 v82, 0xbfb8aa3b, v76
	v_mul_f32_e32 v83, 0xbfb8aa3b, v77
	v_exp_f32_e32 v82, v82
	v_exp_f32_e32 v83, v83
	global_store_dwordx2 v[96:97], v[80:81], off offset:32
	v_or_b32_e32 v80, 48, v122
	v_add_f32_e32 v82, 1.0, v82
	v_add_f32_e32 v83, 1.0, v83
	v_rcp_f32_e32 v82, v82
	v_rcp_f32_e32 v83, v83
	v_mad_i64_i32 v[80:81], s[2:3], v80, s46, v[120:121]
	v_pk_mul_f32 v[76:77], v[76:77], v[82:83]
	s_nop 0
	v_pk_mul_f32 v[72:73], v[72:73], v[76:77]
	s_nop 0
	v_cvt_pk_bf16_f32 v72, v72, v73
	v_mul_f32_e32 v73, 0xbfb8aa3b, v78
	v_exp_f32_e32 v73, v73
	s_nop 0
	v_add_f32_e32 v73, 1.0, v73
	v_rcp_f32_e32 v76, v73
	v_mul_f32_e32 v73, 0xbfb8aa3b, v79
	v_exp_f32_e32 v73, v73
	s_nop 0
	v_add_f32_e32 v73, 1.0, v73
	v_rcp_f32_e32 v77, v73
	s_nop 0
	v_pk_mul_f32 v[76:77], v[78:79], v[76:77]
	s_nop 0
	v_pk_mul_f32 v[74:75], v[74:75], v[76:77]
	s_nop 0
	v_cvt_pk_bf16_f32 v73, v74, v75
	global_store_dwordx2 v[80:81], v[72:73], off
	v_mul_f32_e32 v72, 0xbfb8aa3b, v68
	v_mul_f32_e32 v73, 0xbfb8aa3b, v69
	v_exp_f32_e32 v72, v72
	v_exp_f32_e32 v73, v73
	v_add_f32_e32 v72, 1.0, v72
	v_add_f32_e32 v73, 1.0, v73
	v_rcp_f32_e32 v72, v72
	v_rcp_f32_e32 v73, v73
	s_nop 0
	v_pk_mul_f32 v[68:69], v[68:69], v[72:73]
	s_nop 0
	v_pk_mul_f32 v[64:65], v[64:65], v[68:69]
	s_nop 0
	v_cvt_pk_bf16_f32 v64, v64, v65
	v_mul_f32_e32 v65, 0xbfb8aa3b, v70
	v_exp_f32_e32 v65, v65
	s_nop 0
	v_add_f32_e32 v65, 1.0, v65
	v_rcp_f32_e32 v68, v65
	v_mul_f32_e32 v65, 0xbfb8aa3b, v71
	v_exp_f32_e32 v65, v65
	s_nop 0
	v_add_f32_e32 v65, 1.0, v65
	v_rcp_f32_e32 v69, v65
	s_nop 0
	v_pk_mul_f32 v[68:69], v[70:71], v[68:69]
	s_nop 0
	v_pk_mul_f32 v[66:67], v[66:67], v[68:69]
	s_nop 0
	v_cvt_pk_bf16_f32 v65, v66, v67
	v_mul_f32_e32 v66, 0xbfb8aa3b, v60
	v_mul_f32_e32 v67, 0xbfb8aa3b, v61
	v_exp_f32_e32 v66, v66
	v_exp_f32_e32 v67, v67
	global_store_dwordx2 v[80:81], v[64:65], off offset:32
	v_or_b32_e32 v64, 64, v122
	v_add_f32_e32 v66, 1.0, v66
	v_add_f32_e32 v67, 1.0, v67
	v_rcp_f32_e32 v66, v66
	v_rcp_f32_e32 v67, v67
	v_mad_i64_i32 v[64:65], s[2:3], v64, s46, v[120:121]
	v_pk_mul_f32 v[60:61], v[60:61], v[66:67]
	s_nop 0
	v_pk_mul_f32 v[56:57], v[56:57], v[60:61]
	s_nop 0
	v_cvt_pk_bf16_f32 v56, v56, v57
	v_mul_f32_e32 v57, 0xbfb8aa3b, v62
	v_exp_f32_e32 v57, v57
	s_nop 0
	v_add_f32_e32 v57, 1.0, v57
	v_rcp_f32_e32 v60, v57
	v_mul_f32_e32 v57, 0xbfb8aa3b, v63
	v_exp_f32_e32 v57, v57
	s_nop 0
	v_add_f32_e32 v57, 1.0, v57
	v_rcp_f32_e32 v61, v57
	s_nop 0
	v_pk_mul_f32 v[60:61], v[62:63], v[60:61]
	s_nop 0
	v_pk_mul_f32 v[58:59], v[58:59], v[60:61]
	s_nop 0
	v_cvt_pk_bf16_f32 v57, v58, v59
	global_store_dwordx2 v[64:65], v[56:57], off
	v_mul_f32_e32 v56, 0xbfb8aa3b, v52
	v_mul_f32_e32 v57, 0xbfb8aa3b, v53
	v_exp_f32_e32 v56, v56
	v_exp_f32_e32 v57, v57
	v_add_f32_e32 v56, 1.0, v56
	v_add_f32_e32 v57, 1.0, v57
	v_rcp_f32_e32 v56, v56
	v_rcp_f32_e32 v57, v57
	s_nop 0
	v_pk_mul_f32 v[52:53], v[52:53], v[56:57]
	s_nop 0
	v_pk_mul_f32 v[48:49], v[48:49], v[52:53]
	s_nop 0
	v_cvt_pk_bf16_f32 v48, v48, v49
	v_mul_f32_e32 v49, 0xbfb8aa3b, v54
	v_exp_f32_e32 v49, v49
	s_nop 0
	v_add_f32_e32 v49, 1.0, v49
	v_rcp_f32_e32 v52, v49
	v_mul_f32_e32 v49, 0xbfb8aa3b, v55
	v_exp_f32_e32 v49, v49
	s_nop 0
	v_add_f32_e32 v49, 1.0, v49
	v_rcp_f32_e32 v53, v49
	s_nop 0
	v_pk_mul_f32 v[52:53], v[54:55], v[52:53]
	s_nop 0
	v_pk_mul_f32 v[50:51], v[50:51], v[52:53]
	s_nop 0
	v_cvt_pk_bf16_f32 v49, v50, v51
	v_mul_f32_e32 v50, 0xbfb8aa3b, v44
	v_mul_f32_e32 v51, 0xbfb8aa3b, v45
	v_exp_f32_e32 v50, v50
	v_exp_f32_e32 v51, v51
	global_store_dwordx2 v[64:65], v[48:49], off offset:32
	v_or_b32_e32 v48, 0x50, v122
	v_add_f32_e32 v50, 1.0, v50
	v_add_f32_e32 v51, 1.0, v51
	v_rcp_f32_e32 v50, v50
	v_rcp_f32_e32 v51, v51
	v_mad_i64_i32 v[48:49], s[2:3], v48, s46, v[120:121]
	v_pk_mul_f32 v[44:45], v[44:45], v[50:51]
	s_nop 0
	v_pk_mul_f32 v[40:41], v[40:41], v[44:45]
	s_nop 0
	v_cvt_pk_bf16_f32 v40, v40, v41
	v_mul_f32_e32 v41, 0xbfb8aa3b, v46
	v_exp_f32_e32 v41, v41
	s_nop 0
	v_add_f32_e32 v41, 1.0, v41
	v_rcp_f32_e32 v44, v41
	v_mul_f32_e32 v41, 0xbfb8aa3b, v47
	v_exp_f32_e32 v41, v41
	s_nop 0
	v_add_f32_e32 v41, 1.0, v41
	v_rcp_f32_e32 v45, v41
	s_nop 0
	v_pk_mul_f32 v[44:45], v[46:47], v[44:45]
	s_nop 0
	v_pk_mul_f32 v[42:43], v[42:43], v[44:45]
	s_nop 0
	v_cvt_pk_bf16_f32 v41, v42, v43
	global_store_dwordx2 v[48:49], v[40:41], off
	v_mul_f32_e32 v40, 0xbfb8aa3b, v36
	v_mul_f32_e32 v41, 0xbfb8aa3b, v37
	v_exp_f32_e32 v40, v40
	v_exp_f32_e32 v41, v41
	v_add_f32_e32 v40, 1.0, v40
	v_add_f32_e32 v41, 1.0, v41
	v_rcp_f32_e32 v40, v40
	v_rcp_f32_e32 v41, v41
	s_nop 0
	v_pk_mul_f32 v[36:37], v[36:37], v[40:41]
	s_nop 0
	v_pk_mul_f32 v[32:33], v[32:33], v[36:37]
	s_nop 0
	v_cvt_pk_bf16_f32 v32, v32, v33
	v_mul_f32_e32 v33, 0xbfb8aa3b, v38
	v_exp_f32_e32 v33, v33
	s_nop 0
	v_add_f32_e32 v33, 1.0, v33
	v_rcp_f32_e32 v36, v33
	v_mul_f32_e32 v33, 0xbfb8aa3b, v39
	v_exp_f32_e32 v33, v33
	s_nop 0
	v_add_f32_e32 v33, 1.0, v33
	v_rcp_f32_e32 v37, v33
	s_nop 0
	v_pk_mul_f32 v[36:37], v[38:39], v[36:37]
	s_nop 0
	v_pk_mul_f32 v[34:35], v[34:35], v[36:37]
	s_nop 0
	v_cvt_pk_bf16_f32 v33, v34, v35
	v_mul_f32_e32 v34, 0xbfb8aa3b, v28
	v_mul_f32_e32 v35, 0xbfb8aa3b, v29
	v_exp_f32_e32 v34, v34
	v_exp_f32_e32 v35, v35
	global_store_dwordx2 v[48:49], v[32:33], off offset:32
	v_or_b32_e32 v32, 0x60, v122
	v_add_f32_e32 v34, 1.0, v34
	v_add_f32_e32 v35, 1.0, v35
	v_rcp_f32_e32 v34, v34
	v_rcp_f32_e32 v35, v35
	v_mad_i64_i32 v[32:33], s[2:3], v32, s46, v[120:121]
	v_pk_mul_f32 v[28:29], v[28:29], v[34:35]
	s_nop 0
	v_pk_mul_f32 v[24:25], v[24:25], v[28:29]
	s_nop 0
	v_cvt_pk_bf16_f32 v24, v24, v25
	v_mul_f32_e32 v25, 0xbfb8aa3b, v30
	v_exp_f32_e32 v25, v25
	s_nop 0
	v_add_f32_e32 v25, 1.0, v25
	v_rcp_f32_e32 v28, v25
	v_mul_f32_e32 v25, 0xbfb8aa3b, v31
	v_exp_f32_e32 v25, v25
	s_nop 0
	v_add_f32_e32 v25, 1.0, v25
	v_rcp_f32_e32 v29, v25
	s_nop 0
	v_pk_mul_f32 v[28:29], v[30:31], v[28:29]
	s_nop 0
	v_pk_mul_f32 v[26:27], v[26:27], v[28:29]
	s_nop 0
	v_cvt_pk_bf16_f32 v25, v26, v27
	global_store_dwordx2 v[32:33], v[24:25], off
	v_mul_f32_e32 v24, 0xbfb8aa3b, v20
	v_mul_f32_e32 v25, 0xbfb8aa3b, v21
	v_exp_f32_e32 v24, v24
	v_exp_f32_e32 v25, v25
	v_add_f32_e32 v24, 1.0, v24
	v_add_f32_e32 v25, 1.0, v25
	v_rcp_f32_e32 v24, v24
	v_rcp_f32_e32 v25, v25
	s_nop 0
	v_pk_mul_f32 v[20:21], v[20:21], v[24:25]
	s_nop 0
	v_pk_mul_f32 v[16:17], v[16:17], v[20:21]
	s_nop 0
	v_cvt_pk_bf16_f32 v16, v16, v17
	v_mul_f32_e32 v17, 0xbfb8aa3b, v22
	v_exp_f32_e32 v17, v17
	s_nop 0
	v_add_f32_e32 v17, 1.0, v17
	v_rcp_f32_e32 v20, v17
	v_mul_f32_e32 v17, 0xbfb8aa3b, v23
	v_exp_f32_e32 v17, v17
	s_nop 0
	v_add_f32_e32 v17, 1.0, v17
	v_rcp_f32_e32 v21, v17
	s_nop 0
	v_pk_mul_f32 v[20:21], v[22:23], v[20:21]
	s_nop 0
	v_pk_mul_f32 v[18:19], v[18:19], v[20:21]
	s_nop 0
	v_cvt_pk_bf16_f32 v17, v18, v19
	v_mul_f32_e32 v18, 0xbfb8aa3b, v12
	v_mul_f32_e32 v19, 0xbfb8aa3b, v13
	v_exp_f32_e32 v18, v18
	v_exp_f32_e32 v19, v19
	global_store_dwordx2 v[32:33], v[16:17], off offset:32
	v_or_b32_e32 v16, 0x70, v122
	v_add_f32_e32 v18, 1.0, v18
	v_add_f32_e32 v19, 1.0, v19
	v_rcp_f32_e32 v18, v18
	v_rcp_f32_e32 v19, v19
	v_mad_i64_i32 v[16:17], s[2:3], v16, s46, v[120:121]
	v_readlane_b32 s2, v254, 22
	v_pk_mul_f32 v[12:13], v[12:13], v[18:19]
	s_add_i32 s10, s10, s2
	v_pk_mul_f32 v[8:9], v[8:9], v[12:13]
	s_cmpk_gt_u32 s12, 0x15f
	v_cvt_pk_bf16_f32 v8, v8, v9
	v_mul_f32_e32 v9, 0xbfb8aa3b, v14
	v_exp_f32_e32 v9, v9
	s_nop 0
	v_add_f32_e32 v9, 1.0, v9
	v_rcp_f32_e32 v12, v9
	v_mul_f32_e32 v9, 0xbfb8aa3b, v15
	v_exp_f32_e32 v9, v9
	s_nop 0
	v_add_f32_e32 v9, 1.0, v9
	v_rcp_f32_e32 v13, v9
	s_nop 0
	v_pk_mul_f32 v[12:13], v[14:15], v[12:13]
	s_nop 0
	v_pk_mul_f32 v[10:11], v[10:11], v[12:13]
	s_nop 0
	v_cvt_pk_bf16_f32 v9, v10, v11
	global_store_dwordx2 v[16:17], v[8:9], off
	v_mul_f32_e32 v8, 0xbfb8aa3b, v4
	v_mul_f32_e32 v9, 0xbfb8aa3b, v5
	v_exp_f32_e32 v8, v8
	v_exp_f32_e32 v9, v9
	v_add_f32_e32 v8, 1.0, v8
	v_add_f32_e32 v9, 1.0, v9
	v_rcp_f32_e32 v8, v8
	v_rcp_f32_e32 v9, v9
	s_nop 0
	v_pk_mul_f32 v[4:5], v[4:5], v[8:9]
	s_nop 0
	v_pk_mul_f32 v[0:1], v[0:1], v[4:5]
	s_nop 0
	v_cvt_pk_bf16_f32 v0, v0, v1
	v_mul_f32_e32 v1, 0xbfb8aa3b, v6
	v_exp_f32_e32 v1, v1
	s_nop 0
	v_add_f32_e32 v1, 1.0, v1
	v_rcp_f32_e32 v4, v1
	v_mul_f32_e32 v1, 0xbfb8aa3b, v7
	v_exp_f32_e32 v1, v1
	s_nop 0
	v_add_f32_e32 v1, 1.0, v1
	v_rcp_f32_e32 v5, v1
	s_nop 0
	v_pk_mul_f32 v[4:5], v[6:7], v[4:5]
	s_nop 0
	v_pk_mul_f32 v[2:3], v[2:3], v[4:5]
	s_nop 0
	v_cvt_pk_bf16_f32 v1, v2, v3
	global_store_dwordx2 v[16:17], v[0:1], off offset:32
	s_cbranch_scc0 .LBB0_850
